# v77 with the GEMM K-loop s_setprio flips deleted outright and the compiler's duplicate lgkmcnt(0) behind each pre-MFMA barrier removed (the asm wait in front of the barrier already drains LDS)
# speedup vs baseline: 1.0091x; 1.0010x over previous
; #define G_STAGE(bufoff, gbase, voff) do { _Pragma("unroll") for (int _i = 0; _i < 2; ++_i) \
;         __builtin_amdgcn_global_load_lds((const unsigned*)((const char*)(gbase) + (voff)[_i]), (LAS unsigned*)(lds + (bufoff) + ldsw + _i * 8192), 16, 0, 0); } while (0)
; #define G_LDA(dst, b, h) do { _Pragma("unroll") for (int m = 0; m < 4; ++m) { const i32x4 _p0 = *(const LAS i32x4*)(lds + G_SA(b, h) + aoff + m * 2048), _p1 = *(const LAS i32x4*)(lds + G_SA(b, h) + aoff + m * 2048 + 1024); \
;         dst[m] = __builtin_shufflevector(_p0, _p1, 0, 1, 2, 3, 4, 5, 6, 7); } } while (0)
; #define G_LDB(dst, b, h) do { _Pragma("unroll") for (int n = 0; n < 2; ++n) { const i32x4 _p0 = *(const LAS i32x4*)(lds + G_SB(b, h) + boff + n * 2048), _p1 = *(const LAS i32x4*)(lds + G_SB(b, h) + boff + n * 2048 + 1024); \
;         dst[n] = __builtin_shufflevector(_p0, _p1, 0, 1, 2, 3, 4, 5, 6, 7); } } while (0)
; #define G_WAIT_V(n) asm volatile("s_waitcnt vmcnt(" #n ")" ::: "memory")
; #define G_WAIT_L(n) asm volatile("s_waitcnt lgkmcnt(" #n ")" ::: "memory")
; #define G_BAR __builtin_amdgcn_s_barrier()
; #define G_SCHED __builtin_amdgcn_sched_barrier(0)
; template <int NS, int MODE  , class Epi>
; __device__ __forceinline__ void gemm_phase(LAS unsigned char* lds, const Gemm g, const StaticOrder& S, const Epi& E) {
;     ...
;             G_LDB(B0, 0, 0); G_LDB(B1, 0, 1); G_SCHED; G_LDA(At, 0, 0); G_STAGE(G_SA(1, 1), a1 + hstep, voffA);
;             G_WAIT_V(8); G_WAIT_L(0); G_BAR; G_MMA(0, 0, At, B0); G_MMA(0, 1, At, B1); G_BAR; G_SCHED;
;             G_LDA(At, 0, 1); G_STAGE(G_SB(0, 0), b2, voffB); G_STAGE(G_SB(0, 1), b2 + hstep, voffB); G_STAGE(G_SA(0, 0), a2, voffA);
;             G_WAIT_V(8); G_WAIT_L(0); G_BAR; G_MMA(1, 0, At, B0); G_MMA(1, 1, At, B1); G_BAR; G_SCHED;
.LBB0_444:
	s_add_i32 s21, 0, 0x10000
	s_add_i32 s30, 0, 0x14000
	v_add_u32_e32 v132, s21, v190
	v_add_u32_e32 v136, s30, v190
	ds_read_b128 v[160:163], v132
	ds_read_b128 v[148:151], v132 offset:1024
	ds_read_b128 v[156:159], v132 offset:2048
	ds_read_b128 v[152:155], v132 offset:3072
	ds_read_b128 v[144:147], v136
	ds_read_b128 v[132:135], v136 offset:1024
	ds_read_b128 v[140:143], v136 offset:2048
	ds_read_b128 v[136:139], v136 offset:3072
	v_lshl_add_u64 v[176:177], v[174:175], 0, s[60:61]
	s_add_i32 m0, s19, 0xc000
	ds_read_b128 v[202:205], v193
	ds_read_b128 v[206:209], v193 offset:1024
	ds_read_b128 v[210:213], v193 offset:2048
	ds_read_b128 v[214:217], v193 offset:3072
	ds_read_b128 v[218:221], v193 offset:4096
	ds_read_b128 v[222:225], v193 offset:5120
	ds_read_b128 v[226:229], v193 offset:6144
	ds_read_b128 v[242:245], v193 offset:7168
	global_load_lds_dwordx4 v[176:177], off
	v_lshl_add_u64 v[176:177], v[186:187], 0, s[60:61]
	s_add_i32 m0, s19, 0xe000
	s_nop 0
	global_load_lds_dwordx4 v[176:177], off
	s_waitcnt vmcnt(8)
	s_waitcnt lgkmcnt(0)
	s_barrier
	v_mfma_i32_16x16x64_i8 v[128:131], v[160:163], v[202:205], v[128:131]
	v_mfma_i32_16x16x64_i8 v[120:123], v[156:159], v[202:205], v[120:123]
	v_mfma_i32_16x16x64_i8 v[112:115], v[160:163], v[210:213], v[112:115]
	v_mfma_i32_16x16x64_i8 v[104:107], v[156:159], v[210:213], v[104:107]
	v_mfma_i32_16x16x64_i8 v[96:99], v[160:163], v[218:221], v[96:99]
	v_mfma_i32_16x16x64_i8 v[88:91], v[156:159], v[218:221], v[88:91]
	v_mfma_i32_16x16x64_i8 v[80:83], v[160:163], v[226:229], v[80:83]
	v_mfma_i32_16x16x64_i8 v[72:75], v[156:159], v[226:229], v[72:75]
	s_nop 0
	v_mfma_i32_16x16x64_i8 v[128:131], v[148:151], v[206:209], v[128:131]
	v_mfma_i32_16x16x64_i8 v[120:123], v[152:155], v[206:209], v[120:123]
	v_mfma_i32_16x16x64_i8 v[112:115], v[148:151], v[214:217], v[112:115]
	v_mfma_i32_16x16x64_i8 v[104:107], v[152:155], v[214:217], v[104:107]
	v_mfma_i32_16x16x64_i8 v[96:99], v[148:151], v[222:225], v[96:99]
	v_mfma_i32_16x16x64_i8 v[88:91], v[152:155], v[222:225], v[88:91]
	v_mfma_i32_16x16x64_i8 v[80:83], v[148:151], v[242:245], v[80:83]
	v_mfma_i32_16x16x64_i8 v[72:75], v[152:155], v[242:245], v[72:75]
	v_mfma_i32_16x16x64_i8 v[124:127], v[144:147], v[202:205], v[124:127]
	v_mfma_i32_16x16x64_i8 v[116:119], v[140:143], v[202:205], v[116:119]
	v_mfma_i32_16x16x64_i8 v[108:111], v[144:147], v[210:213], v[108:111]
	v_mfma_i32_16x16x64_i8 v[100:103], v[140:143], v[210:213], v[100:103]
	v_mfma_i32_16x16x64_i8 v[92:95], v[144:147], v[218:221], v[92:95]
	v_mfma_i32_16x16x64_i8 v[84:87], v[140:143], v[218:221], v[84:87]
	v_mfma_i32_16x16x64_i8 v[76:79], v[144:147], v[226:229], v[76:79]
	v_mfma_i32_16x16x64_i8 v[68:71], v[140:143], v[226:229], v[68:71]
	s_nop 0
	v_mfma_i32_16x16x64_i8 v[124:127], v[132:135], v[206:209], v[124:127]
	v_mfma_i32_16x16x64_i8 v[116:119], v[136:139], v[206:209], v[116:119]
	v_mfma_i32_16x16x64_i8 v[108:111], v[132:135], v[214:217], v[108:111]
	v_mfma_i32_16x16x64_i8 v[100:103], v[136:139], v[214:217], v[100:103]
	v_mfma_i32_16x16x64_i8 v[92:95], v[132:135], v[222:225], v[92:95]
	v_mfma_i32_16x16x64_i8 v[84:87], v[136:139], v[222:225], v[84:87]
	v_mfma_i32_16x16x64_i8 v[76:79], v[132:135], v[242:245], v[76:79]
	v_mfma_i32_16x16x64_i8 v[68:71], v[136:139], v[242:245], v[68:71]
	s_barrier
	s_add_i32 s21, s21, s18
	v_lshl_add_u64 v[176:177], s[68:69], 0, v[2:3]
	s_mov_b32 m0, s21
	ds_read_b128 v[202:205], v193 offset:16384
	ds_read_b128 v[206:209], v193 offset:17408
	ds_read_b128 v[210:213], v193 offset:18432
	ds_read_b128 v[214:217], v193 offset:19456
	ds_read_b128 v[218:221], v193 offset:20480
	ds_read_b128 v[222:225], v193 offset:21504
	ds_read_b128 v[226:229], v193 offset:22528
	ds_read_b128 v[242:245], v193 offset:23552
	global_load_lds_dwordx4 v[176:177], off
	s_add_i32 m0, s21, 0x2000
	s_add_u32 s24, s68, 0x40000
	v_lshl_add_u64 v[176:177], s[68:69], 0, v[164:165]
	s_addc_u32 s25, s69, 0
	s_add_i32 s21, s30, s18
	global_load_lds_dwordx4 v[176:177], off
	v_lshl_add_u64 v[176:177], s[24:25], 0, v[2:3]
	s_mov_b32 m0, s21
	s_nop 0
	global_load_lds_dwordx4 v[176:177], off
	v_lshl_add_u64 v[176:177], s[24:25], 0, v[164:165]
	s_add_i32 m0, s21, 0x2000
	s_nop 0
	global_load_lds_dwordx4 v[176:177], off
	v_lshl_add_u64 v[176:177], s[66:67], 0, v[168:169]
	s_mov_b32 m0, s19
	s_nop 0
	global_load_lds_dwordx4 v[176:177], off
	v_lshl_add_u64 v[176:177], s[66:67], 0, v[166:167]
	s_mov_b32 m0, s29
	s_nop 0
	global_load_lds_dwordx4 v[176:177], off
	s_waitcnt vmcnt(8)
	s_waitcnt lgkmcnt(0)
	s_barrier
	v_mfma_i32_16x16x64_i8 v[64:67], v[160:163], v[202:205], v[64:67]
	v_mfma_i32_16x16x64_i8 v[56:59], v[156:159], v[202:205], v[56:59]
	v_mfma_i32_16x16x64_i8 v[48:51], v[160:163], v[210:213], v[48:51]
	v_mfma_i32_16x16x64_i8 v[40:43], v[156:159], v[210:213], v[40:43]
	v_mfma_i32_16x16x64_i8 v[32:35], v[160:163], v[218:221], v[32:35]
	v_mfma_i32_16x16x64_i8 v[24:27], v[156:159], v[218:221], v[24:27]
	v_mfma_i32_16x16x64_i8 v[16:19], v[160:163], v[226:229], v[16:19]
	v_mfma_i32_16x16x64_i8 v[8:11], v[156:159], v[226:229], v[8:11]
	s_nop 0
	v_mfma_i32_16x16x64_i8 v[64:67], v[148:151], v[206:209], v[64:67]
	v_mfma_i32_16x16x64_i8 v[56:59], v[152:155], v[206:209], v[56:59]
	v_mfma_i32_16x16x64_i8 v[48:51], v[148:151], v[214:217], v[48:51]
	v_mfma_i32_16x16x64_i8 v[40:43], v[152:155], v[214:217], v[40:43]
	v_mfma_i32_16x16x64_i8 v[32:35], v[148:151], v[222:225], v[32:35]
	v_mfma_i32_16x16x64_i8 v[24:27], v[152:155], v[222:225], v[24:27]
	v_mfma_i32_16x16x64_i8 v[16:19], v[148:151], v[242:245], v[16:19]
	v_mfma_i32_16x16x64_i8 v[8:11], v[152:155], v[242:245], v[8:11]
	v_mfma_i32_16x16x64_i8 v[60:63], v[144:147], v[202:205], v[60:63]
	v_mfma_i32_16x16x64_i8 v[52:55], v[140:143], v[202:205], v[52:55]
	v_mfma_i32_16x16x64_i8 v[44:47], v[144:147], v[210:213], v[44:47]
	v_mfma_i32_16x16x64_i8 v[36:39], v[140:143], v[210:213], v[36:39]
	v_mfma_i32_16x16x64_i8 v[28:31], v[144:147], v[218:221], v[28:31]
	v_mfma_i32_16x16x64_i8 v[20:23], v[140:143], v[218:221], v[20:23]
	v_mfma_i32_16x16x64_i8 v[12:15], v[144:147], v[226:229], v[12:15]
	v_mfma_i32_16x16x64_i8 v[4:7], v[140:143], v[226:229], v[4:7]
	s_nop 0
	v_mfma_i32_16x16x64_i8 v[60:63], v[132:135], v[206:209], v[60:63]
	v_mfma_i32_16x16x64_i8 v[52:55], v[136:139], v[206:209], v[52:55]
	v_mfma_i32_16x16x64_i8 v[44:47], v[132:135], v[214:217], v[44:47]
	v_mfma_i32_16x16x64_i8 v[36:39], v[136:139], v[214:217], v[36:39]
	v_mfma_i32_16x16x64_i8 v[28:31], v[132:135], v[222:225], v[28:31]
	v_mfma_i32_16x16x64_i8 v[20:23], v[136:139], v[222:225], v[20:23]
	v_mfma_i32_16x16x64_i8 v[12:15], v[132:135], v[242:245], v[12:15]
	v_mfma_i32_16x16x64_i8 v[4:7], v[136:139], v[242:245], v[4:7]
	s_barrier
; #define G_STAGE(bufoff, gbase, voff) do { _Pragma("unroll") for (int _i = 0; _i < 2; ++_i) \
;         __builtin_amdgcn_global_load_lds((const unsigned*)((const char*)(gbase) + (voff)[_i]), (LAS unsigned*)(lds + (bufoff) + ldsw + _i * 8192), 16, 0, 0); } while (0)
; #define G_LDA(dst, b, h) do { _Pragma("unroll") for (int m = 0; m < 4; ++m) { const i32x4 _p0 = *(const LAS i32x4*)(lds + G_SA(b, h) + aoff + m * 2048), _p1 = *(const LAS i32x4*)(lds + G_SA(b, h) + aoff + m * 2048 + 1024); \
;         dst[m] = __builtin_shufflevector(_p0, _p1, 0, 1, 2, 3, 4, 5, 6, 7); } } while (0)
; #define G_LDB(dst, b, h) do { _Pragma("unroll") for (int n = 0; n < 2; ++n) { const i32x4 _p0 = *(const LAS i32x4*)(lds + G_SB(b, h) + boff + n * 2048), _p1 = *(const LAS i32x4*)(lds + G_SB(b, h) + boff + n * 2048 + 1024); \
;         dst[n] = __builtin_shufflevector(_p0, _p1, 0, 1, 2, 3, 4, 5, 6, 7); } } while (0)
; #define G_WAIT_V(n) asm volatile("s_waitcnt vmcnt(" #n ")" ::: "memory")
; #define G_WAIT_L(n) asm volatile("s_waitcnt lgkmcnt(" #n ")" ::: "memory")
; #define G_BAR __builtin_amdgcn_s_barrier()
; #define G_SCHED __builtin_amdgcn_sched_barrier(0)
; template <int NS, int MODE  , class Epi>
; __device__ __forceinline__ void gemm_phase(LAS unsigned char* lds, const Gemm g, const StaticOrder& S, const Epi& E) {
;     ...
;             G_LDB(B0, 1, 0); G_LDB(B1, 1, 1); G_SCHED; G_LDA(At, 1, 0); G_STAGE(G_SA(0, 1), a2 + hstep, voffA);
;             G_WAIT_V(8); G_WAIT_L(0); G_BAR; G_MMA(0, 0, At, B0); G_MMA(0, 1, At, B1); G_BAR; G_SCHED;
;             G_LDA(At, 1, 1); G_STAGE(G_SB(1, 0), b3, voffB); G_STAGE(G_SB(1, 1), b3 + hstep, voffB); G_STAGE(G_SA(1, 0), a3, voffA);
;             G_WAIT_V(8); G_WAIT_L(0); G_BAR; G_MMA(1, 0, At, B0); G_MMA(1, 1, At, B1); G_BAR; G_SCHED;
	s_add_i32 s21, 0, 0x18000
	s_add_i32 s30, 0, 0x1c000
	v_add_u32_e32 v144, s21, v190
	v_add_u32_e32 v160, s30, v190
	ds_read_b128 v[132:135], v144
	ds_read_b128 v[136:139], v144 offset:1024
	ds_read_b128 v[140:143], v144 offset:2048
	ds_read_b128 v[144:147], v144 offset:3072
	ds_read_b128 v[148:151], v160
	ds_read_b128 v[152:155], v160 offset:1024
	ds_read_b128 v[156:159], v160 offset:2048
	ds_read_b128 v[160:163], v160 offset:3072
	s_add_u32 s24, s66, 0x40000
	s_addc_u32 s25, s67, 0
	s_mov_b32 m0, s56
	v_lshl_add_u64 v[176:177], s[24:25], 0, v[168:169]
	ds_read_b128 v[202:205], v193 offset:32768
	ds_read_b128 v[206:209], v193 offset:33792
	ds_read_b128 v[210:213], v193 offset:34816
	ds_read_b128 v[214:217], v193 offset:35840
	ds_read_b128 v[218:221], v193 offset:36864
	ds_read_b128 v[222:225], v193 offset:37888
	ds_read_b128 v[226:229], v193 offset:38912
	ds_read_b128 v[242:245], v193 offset:39936
	global_load_lds_dwordx4 v[176:177], off
	v_lshl_add_u64 v[176:177], s[24:25], 0, v[166:167]
	s_mov_b32 m0, s70
	s_nop 0
	global_load_lds_dwordx4 v[176:177], off
	s_waitcnt vmcnt(8)
	s_waitcnt lgkmcnt(0)
	s_barrier
	v_mfma_i32_16x16x64_i8 v[128:131], v[132:135], v[202:205], v[128:131]
	v_mfma_i32_16x16x64_i8 v[120:123], v[140:143], v[202:205], v[120:123]
	v_mfma_i32_16x16x64_i8 v[112:115], v[132:135], v[210:213], v[112:115]
	v_mfma_i32_16x16x64_i8 v[104:107], v[140:143], v[210:213], v[104:107]
	v_mfma_i32_16x16x64_i8 v[96:99], v[132:135], v[218:221], v[96:99]
	v_mfma_i32_16x16x64_i8 v[88:91], v[140:143], v[218:221], v[88:91]
	v_mfma_i32_16x16x64_i8 v[80:83], v[132:135], v[226:229], v[80:83]
	v_mfma_i32_16x16x64_i8 v[72:75], v[140:143], v[226:229], v[72:75]
	s_nop 0
	v_mfma_i32_16x16x64_i8 v[128:131], v[136:139], v[206:209], v[128:131]
	v_mfma_i32_16x16x64_i8 v[120:123], v[144:147], v[206:209], v[120:123]
	v_mfma_i32_16x16x64_i8 v[112:115], v[136:139], v[214:217], v[112:115]
	v_mfma_i32_16x16x64_i8 v[104:107], v[144:147], v[214:217], v[104:107]
	v_mfma_i32_16x16x64_i8 v[96:99], v[136:139], v[222:225], v[96:99]
	v_mfma_i32_16x16x64_i8 v[88:91], v[144:147], v[222:225], v[88:91]
	v_mfma_i32_16x16x64_i8 v[80:83], v[136:139], v[242:245], v[80:83]
	v_mfma_i32_16x16x64_i8 v[72:75], v[144:147], v[242:245], v[72:75]
	v_mfma_i32_16x16x64_i8 v[124:127], v[148:151], v[202:205], v[124:127]
	v_mfma_i32_16x16x64_i8 v[116:119], v[156:159], v[202:205], v[116:119]
	v_mfma_i32_16x16x64_i8 v[108:111], v[148:151], v[210:213], v[108:111]
	v_mfma_i32_16x16x64_i8 v[100:103], v[156:159], v[210:213], v[100:103]
	v_mfma_i32_16x16x64_i8 v[92:95], v[148:151], v[218:221], v[92:95]
	v_mfma_i32_16x16x64_i8 v[84:87], v[156:159], v[218:221], v[84:87]
	v_mfma_i32_16x16x64_i8 v[76:79], v[148:151], v[226:229], v[76:79]
	v_mfma_i32_16x16x64_i8 v[68:71], v[156:159], v[226:229], v[68:71]
	s_nop 0
	v_mfma_i32_16x16x64_i8 v[124:127], v[152:155], v[206:209], v[124:127]
	v_mfma_i32_16x16x64_i8 v[116:119], v[160:163], v[206:209], v[116:119]
	v_mfma_i32_16x16x64_i8 v[108:111], v[152:155], v[214:217], v[108:111]
	v_mfma_i32_16x16x64_i8 v[100:103], v[160:163], v[214:217], v[100:103]
	v_mfma_i32_16x16x64_i8 v[92:95], v[152:155], v[222:225], v[92:95]
	v_mfma_i32_16x16x64_i8 v[84:87], v[160:163], v[222:225], v[84:87]
	v_mfma_i32_16x16x64_i8 v[76:79], v[152:155], v[242:245], v[76:79]
	v_mfma_i32_16x16x64_i8 v[68:71], v[160:163], v[242:245], v[68:71]
	s_barrier
	s_add_i32 s21, s21, s18
	v_lshl_add_u64 v[176:177], s[64:65], 0, v[2:3]
	s_mov_b32 m0, s21
	ds_read_b128 v[202:205], v193 offset:49152
	ds_read_b128 v[206:209], v193 offset:50176
	ds_read_b128 v[210:213], v193 offset:51200
	ds_read_b128 v[214:217], v193 offset:52224
	ds_read_b128 v[218:221], v193 offset:53248
	ds_read_b128 v[222:225], v193 offset:54272
	ds_read_b128 v[226:229], v193 offset:55296
	ds_read_b128 v[242:245], v193 offset:56320
	global_load_lds_dwordx4 v[176:177], off
	s_add_i32 m0, s21, 0x2000
	s_add_u32 s24, s64, 0x40000
	v_lshl_add_u64 v[176:177], s[64:65], 0, v[164:165]
	s_addc_u32 s25, s65, 0
	s_add_i32 s21, s30, s18
	global_load_lds_dwordx4 v[176:177], off
	v_lshl_add_u64 v[176:177], s[24:25], 0, v[2:3]
	s_mov_b32 m0, s21
	s_nop 0
	global_load_lds_dwordx4 v[176:177], off
	v_lshl_add_u64 v[176:177], s[24:25], 0, v[164:165]
	s_add_i32 m0, s21, 0x2000
	s_nop 0
	global_load_lds_dwordx4 v[176:177], off
	v_lshl_add_u64 v[176:177], s[62:63], 0, v[168:169]
	s_mov_b32 m0, s71
	s_nop 0
	global_load_lds_dwordx4 v[176:177], off
	v_lshl_add_u64 v[176:177], s[62:63], 0, v[166:167]
	s_mov_b32 m0, s72
	s_nop 0
	global_load_lds_dwordx4 v[176:177], off
	s_waitcnt vmcnt(8)
	s_waitcnt lgkmcnt(0)
	s_barrier
	v_mfma_i32_16x16x64_i8 v[64:67], v[132:135], v[202:205], v[64:67]
	v_mfma_i32_16x16x64_i8 v[56:59], v[140:143], v[202:205], v[56:59]
	v_mfma_i32_16x16x64_i8 v[48:51], v[132:135], v[210:213], v[48:51]
	v_mfma_i32_16x16x64_i8 v[40:43], v[140:143], v[210:213], v[40:43]
	v_mfma_i32_16x16x64_i8 v[32:35], v[132:135], v[218:221], v[32:35]
	v_mfma_i32_16x16x64_i8 v[24:27], v[140:143], v[218:221], v[24:27]
	v_mfma_i32_16x16x64_i8 v[16:19], v[132:135], v[226:229], v[16:19]
	v_mfma_i32_16x16x64_i8 v[8:11], v[140:143], v[226:229], v[8:11]
	s_nop 0
	v_mfma_i32_16x16x64_i8 v[64:67], v[136:139], v[206:209], v[64:67]
	v_mfma_i32_16x16x64_i8 v[56:59], v[144:147], v[206:209], v[56:59]
	v_mfma_i32_16x16x64_i8 v[48:51], v[136:139], v[214:217], v[48:51]
	v_mfma_i32_16x16x64_i8 v[40:43], v[144:147], v[214:217], v[40:43]
	v_mfma_i32_16x16x64_i8 v[32:35], v[136:139], v[222:225], v[32:35]
	v_mfma_i32_16x16x64_i8 v[24:27], v[144:147], v[222:225], v[24:27]
	v_mfma_i32_16x16x64_i8 v[16:19], v[136:139], v[242:245], v[16:19]
	v_mfma_i32_16x16x64_i8 v[8:11], v[144:147], v[242:245], v[8:11]
	v_mfma_i32_16x16x64_i8 v[60:63], v[148:151], v[202:205], v[60:63]
	v_mfma_i32_16x16x64_i8 v[52:55], v[156:159], v[202:205], v[52:55]
	v_mfma_i32_16x16x64_i8 v[44:47], v[148:151], v[210:213], v[44:47]
	v_mfma_i32_16x16x64_i8 v[36:39], v[156:159], v[210:213], v[36:39]
	v_mfma_i32_16x16x64_i8 v[28:31], v[148:151], v[218:221], v[28:31]
	v_mfma_i32_16x16x64_i8 v[20:23], v[156:159], v[218:221], v[20:23]
	v_mfma_i32_16x16x64_i8 v[12:15], v[148:151], v[226:229], v[12:15]
	v_mfma_i32_16x16x64_i8 v[4:7], v[156:159], v[226:229], v[4:7]
	s_nop 0
	v_mfma_i32_16x16x64_i8 v[60:63], v[152:155], v[206:209], v[60:63]
	v_mfma_i32_16x16x64_i8 v[52:55], v[160:163], v[206:209], v[52:55]
	v_mfma_i32_16x16x64_i8 v[44:47], v[152:155], v[214:217], v[44:47]
	v_mfma_i32_16x16x64_i8 v[36:39], v[160:163], v[214:217], v[36:39]
	v_mfma_i32_16x16x64_i8 v[28:31], v[152:155], v[222:225], v[28:31]
	v_mfma_i32_16x16x64_i8 v[20:23], v[160:163], v[222:225], v[20:23]
	v_mfma_i32_16x16x64_i8 v[12:15], v[152:155], v[242:245], v[12:15]
	v_mfma_i32_16x16x64_i8 v[4:7], v[160:163], v[242:245], v[4:7]
	s_barrier
	s_add_i32 s13, s13, 2
	s_add_u32 s60, s60, 0x100
	s_addc_u32 s61, s61, 0
	s_cmp_gt_u32 s13, 13
	s_cbranch_scc1 .LBB0_447

; #define G_STAGE(bufoff, gbase, voff) do { _Pragma("unroll") for (int _i = 0; _i < 2; ++_i) \
;         __builtin_amdgcn_global_load_lds((const unsigned*)((const char*)(gbase) + (voff)[_i]), (LAS unsigned*)(lds + (bufoff) + ldsw + _i * 8192), 16, 0, 0); } while (0)
; #define G_LDA(dst, b, h) do { _Pragma("unroll") for (int m = 0; m < 4; ++m) { const i32x4 _p0 = *(const LAS i32x4*)(lds + G_SA(b, h) + aoff + m * 2048), _p1 = *(const LAS i32x4*)(lds + G_SA(b, h) + aoff + m * 2048 + 1024); \
;         dst[m] = __builtin_shufflevector(_p0, _p1, 0, 1, 2, 3, 4, 5, 6, 7); } } while (0)
; #define G_LDB(dst, b, h) do { _Pragma("unroll") for (int n = 0; n < 2; ++n) { const i32x4 _p0 = *(const LAS i32x4*)(lds + G_SB(b, h) + boff + n * 2048), _p1 = *(const LAS i32x4*)(lds + G_SB(b, h) + boff + n * 2048 + 1024); \
;         dst[n] = __builtin_shufflevector(_p0, _p1, 0, 1, 2, 3, 4, 5, 6, 7); } } while (0)
; #define G_WAIT_V(n) asm volatile("s_waitcnt vmcnt(" #n ")" ::: "memory")
; #define G_WAIT_L(n) asm volatile("s_waitcnt lgkmcnt(" #n ")" ::: "memory")
; #define G_BAR __builtin_amdgcn_s_barrier()
; #define G_SCHED __builtin_amdgcn_sched_barrier(0)
; template <int NS, int MODE  , class Epi>
; __device__ __forceinline__ void gemm_phase(LAS unsigned char* lds, const Gemm g, const StaticOrder& S, const Epi& E) {
;     ...
;             G_LDB(B0, 0, 0); G_LDB(B1, 0, 1); G_SCHED; G_LDA(At, 0, 0); G_STAGE(G_SA(1, 1), a1 + hstep, voffA);
;             G_WAIT_V(8); G_WAIT_L(0); G_BAR; G_MMA(0, 0, At, B0); G_MMA(0, 1, At, B1); G_BAR; G_SCHED;
;             G_LDA(At, 0, 1); G_STAGE(G_SB(0, 0), b2, voffB); G_STAGE(G_SB(0, 1), b2 + hstep, voffB); G_STAGE(G_SA(0, 0), a2, voffA);
;             G_WAIT_V(8); G_WAIT_L(0); G_BAR; G_MMA(1, 0, At, B0); G_MMA(1, 1, At, B1); G_BAR; G_SCHED;
.LBB0_525:
	s_add_i32 s25, 0, 0x10000
	s_add_i32 s30, 0, 0x14000
	v_add_u32_e32 v4, s25, v244
	v_add_u32_e32 v16, s30, v244
	ds_read_b128 v[20:23], v4
	ds_read_b128 v[24:27], v4 offset:1024
	ds_read_b128 v[28:31], v4 offset:2048
	ds_read_b128 v[32:35], v4 offset:3072
	ds_read_b128 v[4:7], v16
	ds_read_b128 v[8:11], v16 offset:1024
	ds_read_b128 v[12:15], v16 offset:2048
	ds_read_b128 v[16:19], v16 offset:3072
	v_lshl_add_u64 v[176:177], v[164:165], 0, s[46:47]
	s_add_i32 m0, s19, 0xc000
	ds_read_b128 v[168:171], v246
	ds_read_b128 v[172:175], v246 offset:1024
	ds_read_b128 v[196:199], v246 offset:2048
	ds_read_b128 v[200:203], v246 offset:3072
	ds_read_b128 v[204:207], v246 offset:4096
	ds_read_b128 v[208:211], v246 offset:5120
	ds_read_b128 v[212:215], v246 offset:6144
	ds_read_b128 v[216:219], v246 offset:7168
	global_load_lds_dwordx4 v[176:177], off
	v_lshl_add_u64 v[176:177], v[166:167], 0, s[46:47]
	s_add_i32 m0, s19, 0xe000
	s_nop 0
	global_load_lds_dwordx4 v[176:177], off
	s_waitcnt vmcnt(8)
	s_waitcnt lgkmcnt(0)
	s_barrier
	v_mfma_scale_f32_16x16x128_f8f6f4 v[160:163], v[20:27], v[168:175], v[160:163], v242, v242 op_sel_hi:[0,0,0]
	v_mfma_scale_f32_16x16x128_f8f6f4 v[156:159], v[28:35], v[168:175], v[156:159], v242, v242 op_sel_hi:[0,0,0]
	v_mfma_scale_f32_16x16x128_f8f6f4 v[148:151], v[20:27], v[196:203], v[148:151], v242, v242 op_sel_hi:[0,0,0]
	v_mfma_scale_f32_16x16x128_f8f6f4 v[144:147], v[28:35], v[196:203], v[144:147], v242, v242 op_sel_hi:[0,0,0]
	v_mfma_scale_f32_16x16x128_f8f6f4 v[128:131], v[20:27], v[204:211], v[128:131], v242, v242 op_sel_hi:[0,0,0]
	v_mfma_scale_f32_16x16x128_f8f6f4 v[124:127], v[28:35], v[204:211], v[124:127], v242, v242 op_sel_hi:[0,0,0]
	v_mfma_scale_f32_16x16x128_f8f6f4 v[120:123], v[20:27], v[212:219], v[120:123], v242, v242 op_sel_hi:[0,0,0]
	v_mfma_scale_f32_16x16x128_f8f6f4 v[116:119], v[28:35], v[212:219], v[116:119], v242, v242 op_sel_hi:[0,0,0]
	v_mfma_scale_f32_16x16x128_f8f6f4 v[152:155], v[4:11], v[168:175], v[152:155], v242, v242 op_sel_hi:[0,0,0]
	v_mfma_scale_f32_16x16x128_f8f6f4 v[140:143], v[12:19], v[168:175], v[140:143], v242, v242 op_sel_hi:[0,0,0]
	v_mfma_scale_f32_16x16x128_f8f6f4 v[136:139], v[4:11], v[196:203], v[136:139], v242, v242 op_sel_hi:[0,0,0]
	v_mfma_scale_f32_16x16x128_f8f6f4 v[132:135], v[12:19], v[196:203], v[132:135], v242, v242 op_sel_hi:[0,0,0]
	v_mfma_scale_f32_16x16x128_f8f6f4 v[112:115], v[4:11], v[204:211], v[112:115], v242, v242 op_sel_hi:[0,0,0]
	v_mfma_scale_f32_16x16x128_f8f6f4 v[108:111], v[12:19], v[204:211], v[108:111], v242, v242 op_sel_hi:[0,0,0]
	v_mfma_scale_f32_16x16x128_f8f6f4 v[104:107], v[4:11], v[212:219], v[104:107], v242, v242 op_sel_hi:[0,0,0]
	v_mfma_scale_f32_16x16x128_f8f6f4 v[100:103], v[12:19], v[212:219], v[100:103], v242, v242 op_sel_hi:[0,0,0]
	s_barrier
	s_add_i32 s25, s25, s18
	v_lshl_add_u64 v[176:177], s[60:61], 0, v[2:3]
	s_mov_b32 m0, s25
	ds_read_b128 v[168:171], v246 offset:16384
	ds_read_b128 v[172:175], v246 offset:17408
	ds_read_b128 v[196:199], v246 offset:18432
	ds_read_b128 v[200:203], v246 offset:19456
	ds_read_b128 v[204:207], v246 offset:20480
	ds_read_b128 v[208:211], v246 offset:21504
	ds_read_b128 v[212:215], v246 offset:22528
	ds_read_b128 v[216:219], v246 offset:23552
	global_load_lds_dwordx4 v[176:177], off
	s_add_i32 m0, s25, 0x2000
	v_lshl_add_u64 v[176:177], s[60:61], 0, v[186:187]
	s_add_u32 s60, s60, 0xb0000
	s_addc_u32 s61, s61, 0
	s_add_i32 s25, s30, s18
	global_load_lds_dwordx4 v[176:177], off
	v_lshl_add_u64 v[176:177], s[60:61], 0, v[2:3]
	s_mov_b32 m0, s25
	s_nop 0
	global_load_lds_dwordx4 v[176:177], off
	v_lshl_add_u64 v[176:177], s[60:61], 0, v[186:187]
	s_add_i32 m0, s25, 0x2000
	s_nop 0
	global_load_lds_dwordx4 v[176:177], off
	v_lshl_add_u64 v[176:177], s[58:59], 0, v[190:191]
	s_mov_b32 m0, s19
	s_nop 0
	global_load_lds_dwordx4 v[176:177], off
	v_lshl_add_u64 v[176:177], s[58:59], 0, v[188:189]
	s_mov_b32 m0, s29
	s_nop 0
	global_load_lds_dwordx4 v[176:177], off
	s_waitcnt vmcnt(8)
	s_waitcnt lgkmcnt(0)
	s_barrier
	v_mfma_scale_f32_16x16x128_f8f6f4 v[96:99], v[20:27], v[168:175], v[96:99], v242, v242 op_sel_hi:[0,0,0]
	v_mfma_scale_f32_16x16x128_f8f6f4 v[92:95], v[28:35], v[168:175], v[92:95], v242, v242 op_sel_hi:[0,0,0]
	v_mfma_scale_f32_16x16x128_f8f6f4 v[88:91], v[20:27], v[196:203], v[88:91], v242, v242 op_sel_hi:[0,0,0]
	v_mfma_scale_f32_16x16x128_f8f6f4 v[84:87], v[28:35], v[196:203], v[84:87], v242, v242 op_sel_hi:[0,0,0]
	v_mfma_scale_f32_16x16x128_f8f6f4 v[64:67], v[20:27], v[204:211], v[64:67], v242, v242 op_sel_hi:[0,0,0]
	v_mfma_scale_f32_16x16x128_f8f6f4 v[60:63], v[28:35], v[204:211], v[60:63], v242, v242 op_sel_hi:[0,0,0]
	v_mfma_scale_f32_16x16x128_f8f6f4 v[56:59], v[20:27], v[212:219], v[56:59], v242, v242 op_sel_hi:[0,0,0]
	v_mfma_scale_f32_16x16x128_f8f6f4 v[52:55], v[28:35], v[212:219], v[52:55], v242, v242 op_sel_hi:[0,0,0]
	v_mfma_scale_f32_16x16x128_f8f6f4 v[80:83], v[4:11], v[168:175], v[80:83], v242, v242 op_sel_hi:[0,0,0]
	v_mfma_scale_f32_16x16x128_f8f6f4 v[76:79], v[12:19], v[168:175], v[76:79], v242, v242 op_sel_hi:[0,0,0]
	v_mfma_scale_f32_16x16x128_f8f6f4 v[72:75], v[4:11], v[196:203], v[72:75], v242, v242 op_sel_hi:[0,0,0]
	v_mfma_scale_f32_16x16x128_f8f6f4 v[68:71], v[12:19], v[196:203], v[68:71], v242, v242 op_sel_hi:[0,0,0]
	v_mfma_scale_f32_16x16x128_f8f6f4 v[48:51], v[4:11], v[204:211], v[48:51], v242, v242 op_sel_hi:[0,0,0]
	v_mfma_scale_f32_16x16x128_f8f6f4 v[44:47], v[12:19], v[204:211], v[44:47], v242, v242 op_sel_hi:[0,0,0]
	v_mfma_scale_f32_16x16x128_f8f6f4 v[40:43], v[4:11], v[212:219], v[40:43], v242, v242 op_sel_hi:[0,0,0]
	v_mfma_scale_f32_16x16x128_f8f6f4 v[36:39], v[12:19], v[212:219], v[36:39], v242, v242 op_sel_hi:[0,0,0]
	s_barrier
; #define G_STAGE(bufoff, gbase, voff) do { _Pragma("unroll") for (int _i = 0; _i < 2; ++_i) \
;         __builtin_amdgcn_global_load_lds((const unsigned*)((const char*)(gbase) + (voff)[_i]), (LAS unsigned*)(lds + (bufoff) + ldsw + _i * 8192), 16, 0, 0); } while (0)
; #define G_LDA(dst, b, h) do { _Pragma("unroll") for (int m = 0; m < 4; ++m) { const i32x4 _p0 = *(const LAS i32x4*)(lds + G_SA(b, h) + aoff + m * 2048), _p1 = *(const LAS i32x4*)(lds + G_SA(b, h) + aoff + m * 2048 + 1024); \
;         dst[m] = __builtin_shufflevector(_p0, _p1, 0, 1, 2, 3, 4, 5, 6, 7); } } while (0)
; #define G_LDB(dst, b, h) do { _Pragma("unroll") for (int n = 0; n < 2; ++n) { const i32x4 _p0 = *(const LAS i32x4*)(lds + G_SB(b, h) + boff + n * 2048), _p1 = *(const LAS i32x4*)(lds + G_SB(b, h) + boff + n * 2048 + 1024); \
;         dst[n] = __builtin_shufflevector(_p0, _p1, 0, 1, 2, 3, 4, 5, 6, 7); } } while (0)
; #define G_WAIT_V(n) asm volatile("s_waitcnt vmcnt(" #n ")" ::: "memory")
; #define G_WAIT_L(n) asm volatile("s_waitcnt lgkmcnt(" #n ")" ::: "memory")
; #define G_BAR __builtin_amdgcn_s_barrier()
; #define G_SCHED __builtin_amdgcn_sched_barrier(0)
; template <int NS, int MODE  , class Epi>
; __device__ __forceinline__ void gemm_phase(LAS unsigned char* lds, const Gemm g, const StaticOrder& S, const Epi& E) {
;     ...
;             G_LDB(B0, 1, 0); G_LDB(B1, 1, 1); G_SCHED; G_LDA(At, 1, 0); G_STAGE(G_SA(0, 1), a2 + hstep, voffA);
;             G_WAIT_V(8); G_WAIT_L(0); G_BAR; G_MMA(0, 0, At, B0); G_MMA(0, 1, At, B1); G_BAR; G_SCHED;
;             G_LDA(At, 1, 1); G_STAGE(G_SB(1, 0), b3, voffB); G_STAGE(G_SB(1, 1), b3 + hstep, voffB); G_STAGE(G_SA(1, 0), a3, voffA);
;             G_WAIT_V(8); G_WAIT_L(0); G_BAR; G_MMA(1, 0, At, B0); G_MMA(1, 1, At, B1); G_BAR; G_SCHED;
	s_add_i32 s25, 0, 0x18000
	s_add_i32 s35, 0, 0x1c000
	v_add_u32_e32 v16, s25, v244
	v_add_u32_e32 v32, s35, v244
	ds_read_b128 v[4:7], v16
	ds_read_b128 v[8:11], v16 offset:1024
	ds_read_b128 v[12:15], v16 offset:2048
	ds_read_b128 v[16:19], v16 offset:3072
	ds_read_b128 v[20:23], v32
	ds_read_b128 v[24:27], v32 offset:1024
	ds_read_b128 v[28:31], v32 offset:2048
	ds_read_b128 v[32:35], v32 offset:3072
	s_add_u32 s30, s58, 0xb0000
	s_addc_u32 s31, s59, 0
	s_mov_b32 m0, s56
	v_lshl_add_u64 v[176:177], s[30:31], 0, v[190:191]
	ds_read_b128 v[168:171], v246 offset:32768
	ds_read_b128 v[172:175], v246 offset:33792
	ds_read_b128 v[196:199], v246 offset:34816
	ds_read_b128 v[200:203], v246 offset:35840
	ds_read_b128 v[204:207], v246 offset:36864
	ds_read_b128 v[208:211], v246 offset:37888
	ds_read_b128 v[212:215], v246 offset:38912
	ds_read_b128 v[216:219], v246 offset:39936
	global_load_lds_dwordx4 v[176:177], off
	v_lshl_add_u64 v[176:177], s[30:31], 0, v[188:189]
	s_mov_b32 m0, s62
	s_nop 0
	global_load_lds_dwordx4 v[176:177], off
	s_waitcnt vmcnt(8)
	s_waitcnt lgkmcnt(0)
	s_barrier
	v_mfma_scale_f32_16x16x128_f8f6f4 v[160:163], v[4:11], v[168:175], v[160:163], v242, v242 op_sel_hi:[0,0,0]
	v_mfma_scale_f32_16x16x128_f8f6f4 v[156:159], v[12:19], v[168:175], v[156:159], v242, v242 op_sel_hi:[0,0,0]
	v_mfma_scale_f32_16x16x128_f8f6f4 v[148:151], v[4:11], v[196:203], v[148:151], v242, v242 op_sel_hi:[0,0,0]
	v_mfma_scale_f32_16x16x128_f8f6f4 v[144:147], v[12:19], v[196:203], v[144:147], v242, v242 op_sel_hi:[0,0,0]
	v_mfma_scale_f32_16x16x128_f8f6f4 v[128:131], v[4:11], v[204:211], v[128:131], v242, v242 op_sel_hi:[0,0,0]
	v_mfma_scale_f32_16x16x128_f8f6f4 v[124:127], v[12:19], v[204:211], v[124:127], v242, v242 op_sel_hi:[0,0,0]
	v_mfma_scale_f32_16x16x128_f8f6f4 v[120:123], v[4:11], v[212:219], v[120:123], v242, v242 op_sel_hi:[0,0,0]
	v_mfma_scale_f32_16x16x128_f8f6f4 v[116:119], v[12:19], v[212:219], v[116:119], v242, v242 op_sel_hi:[0,0,0]
	v_mfma_scale_f32_16x16x128_f8f6f4 v[152:155], v[20:27], v[168:175], v[152:155], v242, v242 op_sel_hi:[0,0,0]
	v_mfma_scale_f32_16x16x128_f8f6f4 v[140:143], v[28:35], v[168:175], v[140:143], v242, v242 op_sel_hi:[0,0,0]
	v_mfma_scale_f32_16x16x128_f8f6f4 v[136:139], v[20:27], v[196:203], v[136:139], v242, v242 op_sel_hi:[0,0,0]
	v_mfma_scale_f32_16x16x128_f8f6f4 v[132:135], v[28:35], v[196:203], v[132:135], v242, v242 op_sel_hi:[0,0,0]
	v_mfma_scale_f32_16x16x128_f8f6f4 v[112:115], v[20:27], v[204:211], v[112:115], v242, v242 op_sel_hi:[0,0,0]
	v_mfma_scale_f32_16x16x128_f8f6f4 v[108:111], v[28:35], v[204:211], v[108:111], v242, v242 op_sel_hi:[0,0,0]
	v_mfma_scale_f32_16x16x128_f8f6f4 v[104:107], v[20:27], v[212:219], v[104:107], v242, v242 op_sel_hi:[0,0,0]
	v_mfma_scale_f32_16x16x128_f8f6f4 v[100:103], v[28:35], v[212:219], v[100:103], v242, v242 op_sel_hi:[0,0,0]
	s_barrier
	s_add_i32 s25, s25, s18
	v_lshl_add_u64 v[176:177], s[54:55], 0, v[2:3]
	s_mov_b32 m0, s25
	ds_read_b128 v[168:171], v246 offset:49152
	ds_read_b128 v[172:175], v246 offset:50176
	ds_read_b128 v[196:199], v246 offset:51200
	ds_read_b128 v[200:203], v246 offset:52224
	ds_read_b128 v[204:207], v246 offset:53248
	ds_read_b128 v[208:211], v246 offset:54272
	ds_read_b128 v[212:215], v246 offset:55296
	ds_read_b128 v[216:219], v246 offset:56320
	global_load_lds_dwordx4 v[176:177], off
	s_add_i32 m0, s25, 0x2000
	s_add_u32 s30, s54, 0xb0000
	v_lshl_add_u64 v[176:177], s[54:55], 0, v[186:187]
	s_addc_u32 s31, s55, 0
	s_add_i32 s25, s35, s18
	global_load_lds_dwordx4 v[176:177], off
	v_lshl_add_u64 v[176:177], s[30:31], 0, v[2:3]
	s_mov_b32 m0, s25
	s_nop 0
	global_load_lds_dwordx4 v[176:177], off
	v_lshl_add_u64 v[176:177], s[30:31], 0, v[186:187]
	s_add_i32 m0, s25, 0x2000
	s_nop 0
	global_load_lds_dwordx4 v[176:177], off
	v_lshl_add_u64 v[176:177], s[52:53], 0, v[190:191]
	s_mov_b32 m0, s65
	s_nop 0
	global_load_lds_dwordx4 v[176:177], off
	v_lshl_add_u64 v[176:177], s[52:53], 0, v[188:189]
	s_mov_b32 m0, s66
	s_nop 0
	global_load_lds_dwordx4 v[176:177], off
	s_waitcnt vmcnt(8)
	s_waitcnt lgkmcnt(0)
	s_barrier
	v_mfma_scale_f32_16x16x128_f8f6f4 v[96:99], v[4:11], v[168:175], v[96:99], v242, v242 op_sel_hi:[0,0,0]
	v_mfma_scale_f32_16x16x128_f8f6f4 v[92:95], v[12:19], v[168:175], v[92:95], v242, v242 op_sel_hi:[0,0,0]
	v_mfma_scale_f32_16x16x128_f8f6f4 v[88:91], v[4:11], v[196:203], v[88:91], v242, v242 op_sel_hi:[0,0,0]
	v_mfma_scale_f32_16x16x128_f8f6f4 v[84:87], v[12:19], v[196:203], v[84:87], v242, v242 op_sel_hi:[0,0,0]
	v_mfma_scale_f32_16x16x128_f8f6f4 v[64:67], v[4:11], v[204:211], v[64:67], v242, v242 op_sel_hi:[0,0,0]
	v_mfma_scale_f32_16x16x128_f8f6f4 v[60:63], v[12:19], v[204:211], v[60:63], v242, v242 op_sel_hi:[0,0,0]
	v_mfma_scale_f32_16x16x128_f8f6f4 v[56:59], v[4:11], v[212:219], v[56:59], v242, v242 op_sel_hi:[0,0,0]
	v_mfma_scale_f32_16x16x128_f8f6f4 v[52:55], v[12:19], v[212:219], v[52:55], v242, v242 op_sel_hi:[0,0,0]
	v_mfma_scale_f32_16x16x128_f8f6f4 v[80:83], v[20:27], v[168:175], v[80:83], v242, v242 op_sel_hi:[0,0,0]
	v_mfma_scale_f32_16x16x128_f8f6f4 v[76:79], v[28:35], v[168:175], v[76:79], v242, v242 op_sel_hi:[0,0,0]
	v_mfma_scale_f32_16x16x128_f8f6f4 v[72:75], v[20:27], v[196:203], v[72:75], v242, v242 op_sel_hi:[0,0,0]
	v_mfma_scale_f32_16x16x128_f8f6f4 v[68:71], v[28:35], v[196:203], v[68:71], v242, v242 op_sel_hi:[0,0,0]
	v_mfma_scale_f32_16x16x128_f8f6f4 v[48:51], v[20:27], v[204:211], v[48:51], v242, v242 op_sel_hi:[0,0,0]
	v_mfma_scale_f32_16x16x128_f8f6f4 v[44:47], v[28:35], v[204:211], v[44:47], v242, v242 op_sel_hi:[0,0,0]
	v_mfma_scale_f32_16x16x128_f8f6f4 v[40:43], v[20:27], v[212:219], v[40:43], v242, v242 op_sel_hi:[0,0,0]
	v_mfma_scale_f32_16x16x128_f8f6f4 v[36:39], v[28:35], v[212:219], v[36:39], v242, v242 op_sel_hi:[0,0,0]
	s_barrier
	s_add_i32 s24, s24, 2
	s_add_u32 s46, s46, 0x100
	s_addc_u32 s47, s47, 0
	s_cmp_gt_u32 s24, 41
	s_cbranch_scc1 .LBB0_528

; #define G_STAGE(bufoff, gbase, voff) do { _Pragma("unroll") for (int _i = 0; _i < 2; ++_i) \
;         __builtin_amdgcn_global_load_lds((const unsigned*)((const char*)(gbase) + (voff)[_i]), (LAS unsigned*)(lds + (bufoff) + ldsw + _i * 8192), 16, 0, 0); } while (0)
; #define G_LDA(dst, b, h) do { _Pragma("unroll") for (int m = 0; m < 4; ++m) { const i32x4 _p0 = *(const LAS i32x4*)(lds + G_SA(b, h) + aoff + m * 2048), _p1 = *(const LAS i32x4*)(lds + G_SA(b, h) + aoff + m * 2048 + 1024); \
;         dst[m] = __builtin_shufflevector(_p0, _p1, 0, 1, 2, 3, 4, 5, 6, 7); } } while (0)
; #define G_LDB(dst, b, h) do { _Pragma("unroll") for (int n = 0; n < 2; ++n) { const i32x4 _p0 = *(const LAS i32x4*)(lds + G_SB(b, h) + boff + n * 2048), _p1 = *(const LAS i32x4*)(lds + G_SB(b, h) + boff + n * 2048 + 1024); \
;         dst[n] = __builtin_shufflevector(_p0, _p1, 0, 1, 2, 3, 4, 5, 6, 7); } } while (0)
; #define G_WAIT_V(n) asm volatile("s_waitcnt vmcnt(" #n ")" ::: "memory")
; #define G_WAIT_L(n) asm volatile("s_waitcnt lgkmcnt(" #n ")" ::: "memory")
; #define G_BAR __builtin_amdgcn_s_barrier()
; #define G_SCHED __builtin_amdgcn_sched_barrier(0)
; template <int NS, int MODE  , class Epi>
; __device__ __forceinline__ void gemm_phase(LAS unsigned char* lds, const Gemm g, const StaticOrder& S, const Epi& E) {
;     ...
;             G_LDB(B0, 0, 0); G_LDB(B1, 0, 1); G_SCHED; G_LDA(At, 0, 0); G_STAGE(G_SA(1, 1), a1 + hstep, voffA);
;             G_WAIT_V(8); G_WAIT_L(0); G_BAR; G_MMA(0, 0, At, B0); G_MMA(0, 1, At, B1); G_BAR; G_SCHED;
;             G_LDA(At, 0, 1); G_STAGE(G_SB(0, 0), b2, voffB); G_STAGE(G_SB(0, 1), b2 + hstep, voffB); G_STAGE(G_SA(0, 0), a2, voffA);
;             G_WAIT_V(8); G_WAIT_L(0); G_BAR; G_MMA(1, 0, At, B0); G_MMA(1, 1, At, B1); G_BAR; G_SCHED;
.LBB0_733:
	s_add_i32 s25, 0, 0x10000
	s_add_i32 s27, 0, 0x14000
	v_add_u32_e32 v132, s25, v191
	v_add_u32_e32 v136, s27, v191
	ds_read_b128 v[160:163], v132
	ds_read_b128 v[148:151], v132 offset:1024
	ds_read_b128 v[156:159], v132 offset:2048
	ds_read_b128 v[152:155], v132 offset:3072
	ds_read_b128 v[144:147], v136
	ds_read_b128 v[132:135], v136 offset:1024
	ds_read_b128 v[140:143], v136 offset:2048
	ds_read_b128 v[136:139], v136 offset:3072
	v_lshl_add_u64 v[218:219], v[174:175], 0, s[72:73]
	s_add_i32 m0, s19, 0xc000
	ds_read_b128 v[176:179], v193
	ds_read_b128 v[180:183], v193 offset:1024
	ds_read_b128 v[194:197], v193 offset:2048
	ds_read_b128 v[198:201], v193 offset:3072
	ds_read_b128 v[202:205], v193 offset:4096
	ds_read_b128 v[206:209], v193 offset:5120
	ds_read_b128 v[210:213], v193 offset:6144
	ds_read_b128 v[214:217], v193 offset:7168
	global_load_lds_dwordx4 v[218:219], off
	v_lshl_add_u64 v[218:219], v[186:187], 0, s[72:73]
	s_add_i32 m0, s19, 0xe000
	s_nop 0
	global_load_lds_dwordx4 v[218:219], off
	s_waitcnt vmcnt(8)
	s_waitcnt lgkmcnt(0)
	s_barrier
	v_mfma_i32_16x16x64_i8 v[128:131], v[160:163], v[176:179], v[128:131]
	v_mfma_i32_16x16x64_i8 v[124:127], v[156:159], v[176:179], v[124:127]
	v_mfma_i32_16x16x64_i8 v[116:119], v[160:163], v[194:197], v[116:119]
	v_mfma_i32_16x16x64_i8 v[108:111], v[156:159], v[194:197], v[108:111]
	v_mfma_i32_16x16x64_i8 v[100:103], v[160:163], v[202:205], v[100:103]
	v_mfma_i32_16x16x64_i8 v[92:95], v[156:159], v[202:205], v[92:95]
	v_mfma_i32_16x16x64_i8 v[84:87], v[160:163], v[210:213], v[84:87]
	v_mfma_i32_16x16x64_i8 v[76:79], v[156:159], v[210:213], v[76:79]
	s_nop 0
	v_mfma_i32_16x16x64_i8 v[128:131], v[148:151], v[180:183], v[128:131]
	v_mfma_i32_16x16x64_i8 v[124:127], v[152:155], v[180:183], v[124:127]
	v_mfma_i32_16x16x64_i8 v[116:119], v[148:151], v[198:201], v[116:119]
	v_mfma_i32_16x16x64_i8 v[108:111], v[152:155], v[198:201], v[108:111]
	v_mfma_i32_16x16x64_i8 v[100:103], v[148:151], v[206:209], v[100:103]
	v_mfma_i32_16x16x64_i8 v[92:95], v[152:155], v[206:209], v[92:95]
	v_mfma_i32_16x16x64_i8 v[84:87], v[148:151], v[214:217], v[84:87]
	v_mfma_i32_16x16x64_i8 v[76:79], v[152:155], v[214:217], v[76:79]
	v_mfma_i32_16x16x64_i8 v[120:123], v[144:147], v[176:179], v[120:123]
	v_mfma_i32_16x16x64_i8 v[112:115], v[140:143], v[176:179], v[112:115]
	v_mfma_i32_16x16x64_i8 v[104:107], v[144:147], v[194:197], v[104:107]
	v_mfma_i32_16x16x64_i8 v[96:99], v[140:143], v[194:197], v[96:99]
	v_mfma_i32_16x16x64_i8 v[88:91], v[144:147], v[202:205], v[88:91]
	v_mfma_i32_16x16x64_i8 v[80:83], v[140:143], v[202:205], v[80:83]
	v_mfma_i32_16x16x64_i8 v[72:75], v[144:147], v[210:213], v[72:75]
	v_mfma_i32_16x16x64_i8 v[68:71], v[140:143], v[210:213], v[68:71]
	s_nop 0
	v_mfma_i32_16x16x64_i8 v[120:123], v[132:135], v[180:183], v[120:123]
	v_mfma_i32_16x16x64_i8 v[112:115], v[136:139], v[180:183], v[112:115]
	v_mfma_i32_16x16x64_i8 v[104:107], v[132:135], v[198:201], v[104:107]
	v_mfma_i32_16x16x64_i8 v[96:99], v[136:139], v[198:201], v[96:99]
	v_mfma_i32_16x16x64_i8 v[88:91], v[132:135], v[206:209], v[88:91]
	v_mfma_i32_16x16x64_i8 v[80:83], v[136:139], v[206:209], v[80:83]
	v_mfma_i32_16x16x64_i8 v[72:75], v[132:135], v[214:217], v[72:75]
	v_mfma_i32_16x16x64_i8 v[68:71], v[136:139], v[214:217], v[68:71]
	s_barrier
	s_add_i32 s25, s25, s3
	v_lshl_add_u64 v[218:219], s[90:91], 0, v[2:3]
	s_mov_b32 m0, s25
	ds_read_b128 v[176:179], v193 offset:16384
	ds_read_b128 v[180:183], v193 offset:17408
	ds_read_b128 v[194:197], v193 offset:18432
	ds_read_b128 v[198:201], v193 offset:19456
	ds_read_b128 v[202:205], v193 offset:20480
	ds_read_b128 v[206:209], v193 offset:21504
	ds_read_b128 v[210:213], v193 offset:22528
	ds_read_b128 v[214:217], v193 offset:23552
	global_load_lds_dwordx4 v[218:219], off
	s_add_i32 m0, s25, 0x2000
	s_add_u32 s30, s90, 0x40000
	v_lshl_add_u64 v[218:219], s[90:91], 0, v[164:165]
	s_addc_u32 s31, s91, 0
	s_add_i32 s25, s27, s3
	global_load_lds_dwordx4 v[218:219], off
	v_lshl_add_u64 v[218:219], s[30:31], 0, v[2:3]
	s_mov_b32 m0, s25
	s_nop 0
	global_load_lds_dwordx4 v[218:219], off
	v_lshl_add_u64 v[218:219], s[30:31], 0, v[164:165]
	s_add_i32 m0, s25, 0x2000
	s_nop 0
	global_load_lds_dwordx4 v[218:219], off
	v_lshl_add_u64 v[218:219], s[80:81], 0, v[168:169]
	s_mov_b32 m0, s19
	s_nop 0
	global_load_lds_dwordx4 v[218:219], off
	v_lshl_add_u64 v[218:219], s[80:81], 0, v[166:167]
	s_mov_b32 m0, s29
	s_nop 0
	global_load_lds_dwordx4 v[218:219], off
	s_waitcnt vmcnt(8)
	s_waitcnt lgkmcnt(0)
	s_barrier
	v_mfma_i32_16x16x64_i8 v[64:67], v[160:163], v[176:179], v[64:67]
	v_mfma_i32_16x16x64_i8 v[60:63], v[156:159], v[176:179], v[60:63]
	v_mfma_i32_16x16x64_i8 v[52:55], v[160:163], v[194:197], v[52:55]
	v_mfma_i32_16x16x64_i8 v[44:47], v[156:159], v[194:197], v[44:47]
	v_mfma_i32_16x16x64_i8 v[36:39], v[160:163], v[202:205], v[36:39]
	v_mfma_i32_16x16x64_i8 v[28:31], v[156:159], v[202:205], v[28:31]
	v_mfma_i32_16x16x64_i8 v[20:23], v[160:163], v[210:213], v[20:23]
	v_mfma_i32_16x16x64_i8 v[12:15], v[156:159], v[210:213], v[12:15]
	s_nop 0
	v_mfma_i32_16x16x64_i8 v[64:67], v[148:151], v[180:183], v[64:67]
	v_mfma_i32_16x16x64_i8 v[60:63], v[152:155], v[180:183], v[60:63]
	v_mfma_i32_16x16x64_i8 v[52:55], v[148:151], v[198:201], v[52:55]
	v_mfma_i32_16x16x64_i8 v[44:47], v[152:155], v[198:201], v[44:47]
	v_mfma_i32_16x16x64_i8 v[36:39], v[148:151], v[206:209], v[36:39]
	v_mfma_i32_16x16x64_i8 v[28:31], v[152:155], v[206:209], v[28:31]
	v_mfma_i32_16x16x64_i8 v[20:23], v[148:151], v[214:217], v[20:23]
	v_mfma_i32_16x16x64_i8 v[12:15], v[152:155], v[214:217], v[12:15]
	v_mfma_i32_16x16x64_i8 v[56:59], v[144:147], v[176:179], v[56:59]
	v_mfma_i32_16x16x64_i8 v[48:51], v[140:143], v[176:179], v[48:51]
	v_mfma_i32_16x16x64_i8 v[40:43], v[144:147], v[194:197], v[40:43]
	v_mfma_i32_16x16x64_i8 v[32:35], v[140:143], v[194:197], v[32:35]
	v_mfma_i32_16x16x64_i8 v[24:27], v[144:147], v[202:205], v[24:27]
	v_mfma_i32_16x16x64_i8 v[16:19], v[140:143], v[202:205], v[16:19]
	v_mfma_i32_16x16x64_i8 v[8:11], v[144:147], v[210:213], v[8:11]
	v_mfma_i32_16x16x64_i8 v[4:7], v[140:143], v[210:213], v[4:7]
	s_nop 0
	v_mfma_i32_16x16x64_i8 v[56:59], v[132:135], v[180:183], v[56:59]
	v_mfma_i32_16x16x64_i8 v[48:51], v[136:139], v[180:183], v[48:51]
	v_mfma_i32_16x16x64_i8 v[40:43], v[132:135], v[198:201], v[40:43]
	v_mfma_i32_16x16x64_i8 v[32:35], v[136:139], v[198:201], v[32:35]
	v_mfma_i32_16x16x64_i8 v[24:27], v[132:135], v[206:209], v[24:27]
	v_mfma_i32_16x16x64_i8 v[16:19], v[136:139], v[206:209], v[16:19]
	v_mfma_i32_16x16x64_i8 v[8:11], v[132:135], v[214:217], v[8:11]
	v_mfma_i32_16x16x64_i8 v[4:7], v[136:139], v[214:217], v[4:7]
	s_barrier
; #define G_STAGE(bufoff, gbase, voff) do { _Pragma("unroll") for (int _i = 0; _i < 2; ++_i) \
;         __builtin_amdgcn_global_load_lds((const unsigned*)((const char*)(gbase) + (voff)[_i]), (LAS unsigned*)(lds + (bufoff) + ldsw + _i * 8192), 16, 0, 0); } while (0)
; #define G_LDA(dst, b, h) do { _Pragma("unroll") for (int m = 0; m < 4; ++m) { const i32x4 _p0 = *(const LAS i32x4*)(lds + G_SA(b, h) + aoff + m * 2048), _p1 = *(const LAS i32x4*)(lds + G_SA(b, h) + aoff + m * 2048 + 1024); \
;         dst[m] = __builtin_shufflevector(_p0, _p1, 0, 1, 2, 3, 4, 5, 6, 7); } } while (0)
; #define G_LDB(dst, b, h) do { _Pragma("unroll") for (int n = 0; n < 2; ++n) { const i32x4 _p0 = *(const LAS i32x4*)(lds + G_SB(b, h) + boff + n * 2048), _p1 = *(const LAS i32x4*)(lds + G_SB(b, h) + boff + n * 2048 + 1024); \
;         dst[n] = __builtin_shufflevector(_p0, _p1, 0, 1, 2, 3, 4, 5, 6, 7); } } while (0)
; #define G_WAIT_V(n) asm volatile("s_waitcnt vmcnt(" #n ")" ::: "memory")
; #define G_WAIT_L(n) asm volatile("s_waitcnt lgkmcnt(" #n ")" ::: "memory")
; #define G_BAR __builtin_amdgcn_s_barrier()
; #define G_SCHED __builtin_amdgcn_sched_barrier(0)
; template <int NS, int MODE  , class Epi>
; __device__ __forceinline__ void gemm_phase(LAS unsigned char* lds, const Gemm g, const StaticOrder& S, const Epi& E) {
;     ...
;             G_LDB(B0, 1, 0); G_LDB(B1, 1, 1); G_SCHED; G_LDA(At, 1, 0); G_STAGE(G_SA(0, 1), a2 + hstep, voffA);
;             G_WAIT_V(8); G_WAIT_L(0); G_BAR; G_MMA(0, 0, At, B0); G_MMA(0, 1, At, B1); G_BAR; G_SCHED;
;             G_LDA(At, 1, 1); G_STAGE(G_SB(1, 0), b3, voffB); G_STAGE(G_SB(1, 1), b3 + hstep, voffB); G_STAGE(G_SA(1, 0), a3, voffA);
;             G_WAIT_V(8); G_WAIT_L(0); G_BAR; G_MMA(1, 0, At, B0); G_MMA(1, 1, At, B1); G_BAR; G_SCHED;
	s_add_i32 s25, 0, 0x18000
	s_add_i32 s27, 0, 0x1c000
	v_add_u32_e32 v144, s25, v191
	v_add_u32_e32 v160, s27, v191
	ds_read_b128 v[132:135], v144
	ds_read_b128 v[136:139], v144 offset:1024
	ds_read_b128 v[140:143], v144 offset:2048
	ds_read_b128 v[144:147], v144 offset:3072
	ds_read_b128 v[148:151], v160
	ds_read_b128 v[152:155], v160 offset:1024
	ds_read_b128 v[156:159], v160 offset:2048
	ds_read_b128 v[160:163], v160 offset:3072
	s_add_u32 s30, s80, 0x40000
	s_addc_u32 s31, s81, 0
	s_mov_b32 m0, s35
	v_lshl_add_u64 v[218:219], s[30:31], 0, v[168:169]
	ds_read_b128 v[176:179], v193 offset:32768
	ds_read_b128 v[180:183], v193 offset:33792
	ds_read_b128 v[194:197], v193 offset:34816
	ds_read_b128 v[198:201], v193 offset:35840
	ds_read_b128 v[202:205], v193 offset:36864
	ds_read_b128 v[206:209], v193 offset:37888
	ds_read_b128 v[210:213], v193 offset:38912
	ds_read_b128 v[214:217], v193 offset:39936
	global_load_lds_dwordx4 v[218:219], off
	v_lshl_add_u64 v[218:219], s[30:31], 0, v[166:167]
	s_mov_b32 m0, s59
	s_nop 0
	global_load_lds_dwordx4 v[218:219], off
	s_waitcnt vmcnt(8)
	s_waitcnt lgkmcnt(0)
	s_barrier
	v_mfma_i32_16x16x64_i8 v[128:131], v[132:135], v[176:179], v[128:131]
	v_mfma_i32_16x16x64_i8 v[124:127], v[140:143], v[176:179], v[124:127]
	v_mfma_i32_16x16x64_i8 v[116:119], v[132:135], v[194:197], v[116:119]
	v_mfma_i32_16x16x64_i8 v[108:111], v[140:143], v[194:197], v[108:111]
	v_mfma_i32_16x16x64_i8 v[100:103], v[132:135], v[202:205], v[100:103]
	v_mfma_i32_16x16x64_i8 v[92:95], v[140:143], v[202:205], v[92:95]
	v_mfma_i32_16x16x64_i8 v[84:87], v[132:135], v[210:213], v[84:87]
	v_mfma_i32_16x16x64_i8 v[76:79], v[140:143], v[210:213], v[76:79]
	s_nop 0
	v_mfma_i32_16x16x64_i8 v[128:131], v[136:139], v[180:183], v[128:131]
	v_mfma_i32_16x16x64_i8 v[124:127], v[144:147], v[180:183], v[124:127]
	v_mfma_i32_16x16x64_i8 v[116:119], v[136:139], v[198:201], v[116:119]
	v_mfma_i32_16x16x64_i8 v[108:111], v[144:147], v[198:201], v[108:111]
	v_mfma_i32_16x16x64_i8 v[100:103], v[136:139], v[206:209], v[100:103]
	v_mfma_i32_16x16x64_i8 v[92:95], v[144:147], v[206:209], v[92:95]
	v_mfma_i32_16x16x64_i8 v[84:87], v[136:139], v[214:217], v[84:87]
	v_mfma_i32_16x16x64_i8 v[76:79], v[144:147], v[214:217], v[76:79]
	v_mfma_i32_16x16x64_i8 v[120:123], v[148:151], v[176:179], v[120:123]
	v_mfma_i32_16x16x64_i8 v[112:115], v[156:159], v[176:179], v[112:115]
	v_mfma_i32_16x16x64_i8 v[104:107], v[148:151], v[194:197], v[104:107]
	v_mfma_i32_16x16x64_i8 v[96:99], v[156:159], v[194:197], v[96:99]
	v_mfma_i32_16x16x64_i8 v[88:91], v[148:151], v[202:205], v[88:91]
	v_mfma_i32_16x16x64_i8 v[80:83], v[156:159], v[202:205], v[80:83]
	v_mfma_i32_16x16x64_i8 v[72:75], v[148:151], v[210:213], v[72:75]
	v_mfma_i32_16x16x64_i8 v[68:71], v[156:159], v[210:213], v[68:71]
	s_nop 0
	v_mfma_i32_16x16x64_i8 v[120:123], v[152:155], v[180:183], v[120:123]
	v_mfma_i32_16x16x64_i8 v[112:115], v[160:163], v[180:183], v[112:115]
	v_mfma_i32_16x16x64_i8 v[104:107], v[152:155], v[198:201], v[104:107]
	v_mfma_i32_16x16x64_i8 v[96:99], v[160:163], v[198:201], v[96:99]
	v_mfma_i32_16x16x64_i8 v[88:91], v[152:155], v[206:209], v[88:91]
	v_mfma_i32_16x16x64_i8 v[80:83], v[160:163], v[206:209], v[80:83]
	v_mfma_i32_16x16x64_i8 v[72:75], v[152:155], v[214:217], v[72:75]
	v_mfma_i32_16x16x64_i8 v[68:71], v[160:163], v[214:217], v[68:71]
	s_barrier
	s_add_i32 s25, s25, s3
	v_lshl_add_u64 v[218:219], s[76:77], 0, v[2:3]
	s_mov_b32 m0, s25
	ds_read_b128 v[176:179], v193 offset:49152
	ds_read_b128 v[180:183], v193 offset:50176
	ds_read_b128 v[194:197], v193 offset:51200
	ds_read_b128 v[198:201], v193 offset:52224
	ds_read_b128 v[202:205], v193 offset:53248
	ds_read_b128 v[206:209], v193 offset:54272
	ds_read_b128 v[210:213], v193 offset:55296
	ds_read_b128 v[214:217], v193 offset:56320
	global_load_lds_dwordx4 v[218:219], off
	s_add_i32 m0, s25, 0x2000
	s_add_u32 s30, s76, 0x40000
	v_lshl_add_u64 v[218:219], s[76:77], 0, v[164:165]
	s_addc_u32 s31, s77, 0
	s_add_i32 s25, s27, s3
	global_load_lds_dwordx4 v[218:219], off
	v_lshl_add_u64 v[218:219], s[30:31], 0, v[2:3]
	s_mov_b32 m0, s25
	s_nop 0
	global_load_lds_dwordx4 v[218:219], off
	v_lshl_add_u64 v[218:219], s[30:31], 0, v[164:165]
	s_add_i32 m0, s25, 0x2000
	s_nop 0
	global_load_lds_dwordx4 v[218:219], off
	v_lshl_add_u64 v[218:219], s[74:75], 0, v[168:169]
	s_mov_b32 m0, s2
	s_nop 0
	global_load_lds_dwordx4 v[218:219], off
	v_lshl_add_u64 v[218:219], s[74:75], 0, v[166:167]
	s_mov_b32 m0, s86
	s_nop 0
	global_load_lds_dwordx4 v[218:219], off
	s_waitcnt vmcnt(8)
	s_waitcnt lgkmcnt(0)
	s_barrier
	v_mfma_i32_16x16x64_i8 v[64:67], v[132:135], v[176:179], v[64:67]
	v_mfma_i32_16x16x64_i8 v[60:63], v[140:143], v[176:179], v[60:63]
	v_mfma_i32_16x16x64_i8 v[52:55], v[132:135], v[194:197], v[52:55]
	v_mfma_i32_16x16x64_i8 v[44:47], v[140:143], v[194:197], v[44:47]
	v_mfma_i32_16x16x64_i8 v[36:39], v[132:135], v[202:205], v[36:39]
	v_mfma_i32_16x16x64_i8 v[28:31], v[140:143], v[202:205], v[28:31]
	v_mfma_i32_16x16x64_i8 v[20:23], v[132:135], v[210:213], v[20:23]
	v_mfma_i32_16x16x64_i8 v[12:15], v[140:143], v[210:213], v[12:15]
	s_nop 0
	v_mfma_i32_16x16x64_i8 v[64:67], v[136:139], v[180:183], v[64:67]
	v_mfma_i32_16x16x64_i8 v[60:63], v[144:147], v[180:183], v[60:63]
	v_mfma_i32_16x16x64_i8 v[52:55], v[136:139], v[198:201], v[52:55]
	v_mfma_i32_16x16x64_i8 v[44:47], v[144:147], v[198:201], v[44:47]
	v_mfma_i32_16x16x64_i8 v[36:39], v[136:139], v[206:209], v[36:39]
	v_mfma_i32_16x16x64_i8 v[28:31], v[144:147], v[206:209], v[28:31]
	v_mfma_i32_16x16x64_i8 v[20:23], v[136:139], v[214:217], v[20:23]
	v_mfma_i32_16x16x64_i8 v[12:15], v[144:147], v[214:217], v[12:15]
	v_mfma_i32_16x16x64_i8 v[56:59], v[148:151], v[176:179], v[56:59]
	v_mfma_i32_16x16x64_i8 v[48:51], v[156:159], v[176:179], v[48:51]
	v_mfma_i32_16x16x64_i8 v[40:43], v[148:151], v[194:197], v[40:43]
	v_mfma_i32_16x16x64_i8 v[32:35], v[156:159], v[194:197], v[32:35]
	v_mfma_i32_16x16x64_i8 v[24:27], v[148:151], v[202:205], v[24:27]
	v_mfma_i32_16x16x64_i8 v[16:19], v[156:159], v[202:205], v[16:19]
	v_mfma_i32_16x16x64_i8 v[8:11], v[148:151], v[210:213], v[8:11]
	v_mfma_i32_16x16x64_i8 v[4:7], v[156:159], v[210:213], v[4:7]
	s_nop 0
	v_mfma_i32_16x16x64_i8 v[56:59], v[152:155], v[180:183], v[56:59]
	v_mfma_i32_16x16x64_i8 v[48:51], v[160:163], v[180:183], v[48:51]
	v_mfma_i32_16x16x64_i8 v[40:43], v[152:155], v[198:201], v[40:43]
	v_mfma_i32_16x16x64_i8 v[32:35], v[160:163], v[198:201], v[32:35]
	v_mfma_i32_16x16x64_i8 v[24:27], v[152:155], v[206:209], v[24:27]
	v_mfma_i32_16x16x64_i8 v[16:19], v[160:163], v[206:209], v[16:19]
	v_mfma_i32_16x16x64_i8 v[8:11], v[152:155], v[214:217], v[8:11]
	v_mfma_i32_16x16x64_i8 v[4:7], v[160:163], v[214:217], v[4:7]
	s_barrier
	s_add_i32 s21, s21, 2
	s_add_u32 s72, s72, 0x100
	s_addc_u32 s73, s73, 0
	s_cmp_gt_u32 s21, 13
	s_cbranch_scc1 .LBB0_736

; #define G_STAGE(bufoff, gbase, voff) do { _Pragma("unroll") for (int _i = 0; _i < 2; ++_i) \
;         __builtin_amdgcn_global_load_lds((const unsigned*)((const char*)(gbase) + (voff)[_i]), (LAS unsigned*)(lds + (bufoff) + ldsw + _i * 8192), 16, 0, 0); } while (0)
; #define G_LDA(dst, b, h) do { _Pragma("unroll") for (int m = 0; m < 4; ++m) { const i32x4 _p0 = *(const LAS i32x4*)(lds + G_SA(b, h) + aoff + m * 2048), _p1 = *(const LAS i32x4*)(lds + G_SA(b, h) + aoff + m * 2048 + 1024); \
;         dst[m] = __builtin_shufflevector(_p0, _p1, 0, 1, 2, 3, 4, 5, 6, 7); } } while (0)
; #define G_LDB(dst, b, h) do { _Pragma("unroll") for (int n = 0; n < 2; ++n) { const i32x4 _p0 = *(const LAS i32x4*)(lds + G_SB(b, h) + boff + n * 2048), _p1 = *(const LAS i32x4*)(lds + G_SB(b, h) + boff + n * 2048 + 1024); \
;         dst[n] = __builtin_shufflevector(_p0, _p1, 0, 1, 2, 3, 4, 5, 6, 7); } } while (0)
; #define G_WAIT_V(n) asm volatile("s_waitcnt vmcnt(" #n ")" ::: "memory")
; #define G_WAIT_L(n) asm volatile("s_waitcnt lgkmcnt(" #n ")" ::: "memory")
; #define G_BAR __builtin_amdgcn_s_barrier()
; #define G_SCHED __builtin_amdgcn_sched_barrier(0)
; template <int NS, int MODE  , class Epi>
; __device__ __forceinline__ void gemm_phase(LAS unsigned char* lds, const Gemm g, const StaticOrder& S, const Epi& E) {
;     ...
;             G_LDB(B0, 0, 0); G_LDB(B1, 0, 1); G_SCHED; G_LDA(At, 0, 0); G_STAGE(G_SA(1, 1), a1 + hstep, voffA);
;             G_WAIT_V(8); G_WAIT_L(0); G_BAR; G_MMA(0, 0, At, B0); G_MMA(0, 1, At, B1); G_BAR; G_SCHED;
;             G_LDA(At, 0, 1); G_STAGE(G_SB(0, 0), b2, voffB); G_STAGE(G_SB(0, 1), b2 + hstep, voffB); G_STAGE(G_SA(0, 0), a2, voffA);
;             G_WAIT_V(8); G_WAIT_L(0); G_BAR; G_MMA(1, 0, At, B0); G_MMA(1, 1, At, B1); G_BAR; G_SCHED;
.LBB0_753:
	s_add_i32 s25, 0, 0x10000
	s_add_i32 s27, 0, 0x14000
	v_add_u32_e32 v162, s25, v147
	v_add_u32_e32 v178, s27, v147
	ds_read_b128 v[150:153], v162
	ds_read_b128 v[154:157], v162 offset:1024
	ds_read_b128 v[158:161], v162 offset:2048
	ds_read_b128 v[162:165], v162 offset:3072
	ds_read_b128 v[166:169], v178
	ds_read_b128 v[170:173], v178 offset:1024
	ds_read_b128 v[174:177], v178 offset:2048
	ds_read_b128 v[178:181], v178 offset:3072
	v_lshl_add_u64 v[182:183], v[142:143], 0, s[72:73]
	s_add_i32 m0, s3, 0xc000
	ds_read_b128 v[190:193], v149
	ds_read_b128 v[194:197], v149 offset:1024
	ds_read_b128 v[198:201], v149 offset:2048
	ds_read_b128 v[202:205], v149 offset:3072
	ds_read_b128 v[206:209], v149 offset:4096
	ds_read_b128 v[210:213], v149 offset:5120
	ds_read_b128 v[214:217], v149 offset:6144
	ds_read_b128 v[218:221], v149 offset:7168
	global_load_lds_dwordx4 v[182:183], off
	v_lshl_add_u64 v[182:183], v[144:145], 0, s[72:73]
	s_add_i32 m0, s3, 0xe000
	s_nop 0
	global_load_lds_dwordx4 v[182:183], off
	s_waitcnt vmcnt(8)
	s_waitcnt lgkmcnt(0)
	s_barrier
	v_mfma_f32_16x16x32_f16 v[128:131], v[150:153], v[190:193], v[128:131]
	v_mfma_f32_16x16x32_f16 v[124:127], v[158:161], v[190:193], v[124:127]
	v_mfma_f32_16x16x32_f16 v[116:119], v[150:153], v[198:201], v[116:119]
	v_mfma_f32_16x16x32_f16 v[108:111], v[158:161], v[198:201], v[108:111]
	v_mfma_f32_16x16x32_f16 v[100:103], v[150:153], v[206:209], v[100:103]
	v_mfma_f32_16x16x32_f16 v[92:95], v[158:161], v[206:209], v[92:95]
	v_mfma_f32_16x16x32_f16 v[84:87], v[150:153], v[214:217], v[84:87]
	v_mfma_f32_16x16x32_f16 v[76:79], v[158:161], v[214:217], v[76:79]
	v_mfma_f32_16x16x32_f16 v[128:131], v[154:157], v[194:197], v[128:131]
	v_mfma_f32_16x16x32_f16 v[124:127], v[162:165], v[194:197], v[124:127]
	v_mfma_f32_16x16x32_f16 v[116:119], v[154:157], v[202:205], v[116:119]
	v_mfma_f32_16x16x32_f16 v[108:111], v[162:165], v[202:205], v[108:111]
	v_mfma_f32_16x16x32_f16 v[100:103], v[154:157], v[210:213], v[100:103]
	v_mfma_f32_16x16x32_f16 v[92:95], v[162:165], v[210:213], v[92:95]
	v_mfma_f32_16x16x32_f16 v[84:87], v[154:157], v[218:221], v[84:87]
	v_mfma_f32_16x16x32_f16 v[76:79], v[162:165], v[218:221], v[76:79]
	v_mfma_f32_16x16x32_f16 v[120:123], v[166:169], v[190:193], v[120:123]
	v_mfma_f32_16x16x32_f16 v[112:115], v[174:177], v[190:193], v[112:115]
	v_mfma_f32_16x16x32_f16 v[104:107], v[166:169], v[198:201], v[104:107]
	v_mfma_f32_16x16x32_f16 v[96:99], v[174:177], v[198:201], v[96:99]
	v_mfma_f32_16x16x32_f16 v[88:91], v[166:169], v[206:209], v[88:91]
	v_mfma_f32_16x16x32_f16 v[80:83], v[174:177], v[206:209], v[80:83]
	v_mfma_f32_16x16x32_f16 v[72:75], v[166:169], v[214:217], v[72:75]
	v_mfma_f32_16x16x32_f16 v[68:71], v[174:177], v[214:217], v[68:71]
	v_mfma_f32_16x16x32_f16 v[120:123], v[170:173], v[194:197], v[120:123]
	v_mfma_f32_16x16x32_f16 v[112:115], v[178:181], v[194:197], v[112:115]
	v_mfma_f32_16x16x32_f16 v[104:107], v[170:173], v[202:205], v[104:107]
	v_mfma_f32_16x16x32_f16 v[96:99], v[178:181], v[202:205], v[96:99]
	v_mfma_f32_16x16x32_f16 v[88:91], v[170:173], v[210:213], v[88:91]
	v_mfma_f32_16x16x32_f16 v[80:83], v[178:181], v[210:213], v[80:83]
	v_mfma_f32_16x16x32_f16 v[72:75], v[170:173], v[218:221], v[72:75]
	v_mfma_f32_16x16x32_f16 v[68:71], v[178:181], v[218:221], v[68:71]
	s_barrier
	s_add_i32 s25, s25, s2
	v_lshl_add_u64 v[182:183], s[90:91], 0, v[2:3]
	s_mov_b32 m0, s25
	ds_read_b128 v[190:193], v149 offset:16384
	ds_read_b128 v[194:197], v149 offset:17408
	ds_read_b128 v[198:201], v149 offset:18432
	ds_read_b128 v[202:205], v149 offset:19456
	ds_read_b128 v[206:209], v149 offset:20480
	ds_read_b128 v[210:213], v149 offset:21504
	ds_read_b128 v[214:217], v149 offset:22528
	ds_read_b128 v[218:221], v149 offset:23552
	global_load_lds_dwordx4 v[182:183], off
	s_add_i32 m0, s25, 0x2000
	s_add_u32 s30, s90, 0x80000
	v_lshl_add_u64 v[182:183], s[90:91], 0, v[132:133]
	s_addc_u32 s31, s91, 0
	s_add_i32 s25, s27, s2
	global_load_lds_dwordx4 v[182:183], off
	v_lshl_add_u64 v[182:183], s[30:31], 0, v[2:3]
	s_mov_b32 m0, s25
	s_nop 0
	global_load_lds_dwordx4 v[182:183], off
	v_lshl_add_u64 v[182:183], s[30:31], 0, v[132:133]
	s_add_i32 m0, s25, 0x2000
	s_nop 0
	global_load_lds_dwordx4 v[182:183], off
	v_lshl_add_u64 v[182:183], s[80:81], 0, v[136:137]
	s_mov_b32 m0, s3
	s_nop 0
	global_load_lds_dwordx4 v[182:183], off
	v_lshl_add_u64 v[182:183], s[80:81], 0, v[134:135]
	s_mov_b32 m0, s18
	s_nop 0
	global_load_lds_dwordx4 v[182:183], off
	s_waitcnt vmcnt(8)
	s_waitcnt lgkmcnt(0)
	s_barrier
	v_mfma_f32_16x16x32_f16 v[64:67], v[150:153], v[190:193], v[64:67]
	v_mfma_f32_16x16x32_f16 v[60:63], v[158:161], v[190:193], v[60:63]
	v_mfma_f32_16x16x32_f16 v[52:55], v[150:153], v[198:201], v[52:55]
	v_mfma_f32_16x16x32_f16 v[44:47], v[158:161], v[198:201], v[44:47]
	v_mfma_f32_16x16x32_f16 v[36:39], v[150:153], v[206:209], v[36:39]
	v_mfma_f32_16x16x32_f16 v[28:31], v[158:161], v[206:209], v[28:31]
	v_mfma_f32_16x16x32_f16 v[20:23], v[150:153], v[214:217], v[20:23]
	v_mfma_f32_16x16x32_f16 v[12:15], v[158:161], v[214:217], v[12:15]
	v_mfma_f32_16x16x32_f16 v[64:67], v[154:157], v[194:197], v[64:67]
	v_mfma_f32_16x16x32_f16 v[60:63], v[162:165], v[194:197], v[60:63]
	v_mfma_f32_16x16x32_f16 v[52:55], v[154:157], v[202:205], v[52:55]
	v_mfma_f32_16x16x32_f16 v[44:47], v[162:165], v[202:205], v[44:47]
	v_mfma_f32_16x16x32_f16 v[36:39], v[154:157], v[210:213], v[36:39]
	v_mfma_f32_16x16x32_f16 v[28:31], v[162:165], v[210:213], v[28:31]
	v_mfma_f32_16x16x32_f16 v[20:23], v[154:157], v[218:221], v[20:23]
	v_mfma_f32_16x16x32_f16 v[12:15], v[162:165], v[218:221], v[12:15]
	v_mfma_f32_16x16x32_f16 v[56:59], v[166:169], v[190:193], v[56:59]
	v_mfma_f32_16x16x32_f16 v[48:51], v[174:177], v[190:193], v[48:51]
	v_mfma_f32_16x16x32_f16 v[40:43], v[166:169], v[198:201], v[40:43]
	v_mfma_f32_16x16x32_f16 v[32:35], v[174:177], v[198:201], v[32:35]
	v_mfma_f32_16x16x32_f16 v[24:27], v[166:169], v[206:209], v[24:27]
	v_mfma_f32_16x16x32_f16 v[16:19], v[174:177], v[206:209], v[16:19]
	v_mfma_f32_16x16x32_f16 v[8:11], v[166:169], v[214:217], v[8:11]
	v_mfma_f32_16x16x32_f16 v[4:7], v[174:177], v[214:217], v[4:7]
	v_mfma_f32_16x16x32_f16 v[56:59], v[170:173], v[194:197], v[56:59]
	v_mfma_f32_16x16x32_f16 v[48:51], v[178:181], v[194:197], v[48:51]
	v_mfma_f32_16x16x32_f16 v[40:43], v[170:173], v[202:205], v[40:43]
	v_mfma_f32_16x16x32_f16 v[32:35], v[178:181], v[202:205], v[32:35]
	v_mfma_f32_16x16x32_f16 v[24:27], v[170:173], v[210:213], v[24:27]
	v_mfma_f32_16x16x32_f16 v[16:19], v[178:181], v[210:213], v[16:19]
	v_mfma_f32_16x16x32_f16 v[8:11], v[170:173], v[218:221], v[8:11]
	v_mfma_f32_16x16x32_f16 v[4:7], v[178:181], v[218:221], v[4:7]
	s_barrier
; #define G_STAGE(bufoff, gbase, voff) do { _Pragma("unroll") for (int _i = 0; _i < 2; ++_i) \
;         __builtin_amdgcn_global_load_lds((const unsigned*)((const char*)(gbase) + (voff)[_i]), (LAS unsigned*)(lds + (bufoff) + ldsw + _i * 8192), 16, 0, 0); } while (0)
; #define G_LDA(dst, b, h) do { _Pragma("unroll") for (int m = 0; m < 4; ++m) { const i32x4 _p0 = *(const LAS i32x4*)(lds + G_SA(b, h) + aoff + m * 2048), _p1 = *(const LAS i32x4*)(lds + G_SA(b, h) + aoff + m * 2048 + 1024); \
;         dst[m] = __builtin_shufflevector(_p0, _p1, 0, 1, 2, 3, 4, 5, 6, 7); } } while (0)
; #define G_LDB(dst, b, h) do { _Pragma("unroll") for (int n = 0; n < 2; ++n) { const i32x4 _p0 = *(const LAS i32x4*)(lds + G_SB(b, h) + boff + n * 2048), _p1 = *(const LAS i32x4*)(lds + G_SB(b, h) + boff + n * 2048 + 1024); \
;         dst[n] = __builtin_shufflevector(_p0, _p1, 0, 1, 2, 3, 4, 5, 6, 7); } } while (0)
; #define G_WAIT_V(n) asm volatile("s_waitcnt vmcnt(" #n ")" ::: "memory")
; #define G_WAIT_L(n) asm volatile("s_waitcnt lgkmcnt(" #n ")" ::: "memory")
; #define G_BAR __builtin_amdgcn_s_barrier()
; #define G_SCHED __builtin_amdgcn_sched_barrier(0)
; template <int NS, int MODE  , class Epi>
; __device__ __forceinline__ void gemm_phase(LAS unsigned char* lds, const Gemm g, const StaticOrder& S, const Epi& E) {
;     ...
;             G_LDB(B0, 1, 0); G_LDB(B1, 1, 1); G_SCHED; G_LDA(At, 1, 0); G_STAGE(G_SA(0, 1), a2 + hstep, voffA);
;             G_WAIT_V(8); G_WAIT_L(0); G_BAR; G_MMA(0, 0, At, B0); G_MMA(0, 1, At, B1); G_BAR; G_SCHED;
;             G_LDA(At, 1, 1); G_STAGE(G_SB(1, 0), b3, voffB); G_STAGE(G_SB(1, 1), b3 + hstep, voffB); G_STAGE(G_SA(1, 0), a3, voffA);
;             G_WAIT_V(8); G_WAIT_L(0); G_BAR; G_MMA(1, 0, At, B0); G_MMA(1, 1, At, B1); G_BAR; G_SCHED;
	s_add_i32 s25, 0, 0x18000
	s_add_i32 s27, 0, 0x1c000
	v_add_u32_e32 v162, s25, v147
	v_add_u32_e32 v178, s27, v147
	ds_read_b128 v[150:153], v162
	ds_read_b128 v[154:157], v162 offset:1024
	ds_read_b128 v[158:161], v162 offset:2048
	ds_read_b128 v[162:165], v162 offset:3072
	ds_read_b128 v[166:169], v178
	ds_read_b128 v[170:173], v178 offset:1024
	ds_read_b128 v[174:177], v178 offset:2048
	ds_read_b128 v[178:181], v178 offset:3072
	s_add_u32 s30, s80, 0x80000
	s_addc_u32 s31, s81, 0
	s_mov_b32 m0, s19
	v_lshl_add_u64 v[182:183], s[30:31], 0, v[136:137]
	ds_read_b128 v[190:193], v149 offset:32768
	ds_read_b128 v[194:197], v149 offset:33792
	ds_read_b128 v[198:201], v149 offset:34816
	ds_read_b128 v[202:205], v149 offset:35840
	ds_read_b128 v[206:209], v149 offset:36864
	ds_read_b128 v[210:213], v149 offset:37888
	ds_read_b128 v[214:217], v149 offset:38912
	ds_read_b128 v[218:221], v149 offset:39936
	global_load_lds_dwordx4 v[182:183], off
	v_lshl_add_u64 v[182:183], s[30:31], 0, v[134:135]
	s_mov_b32 m0, s29
	s_nop 0
	global_load_lds_dwordx4 v[182:183], off
	s_waitcnt vmcnt(8)
	s_waitcnt lgkmcnt(0)
	s_barrier
	v_mfma_f32_16x16x32_f16 v[128:131], v[150:153], v[190:193], v[128:131]
	v_mfma_f32_16x16x32_f16 v[124:127], v[158:161], v[190:193], v[124:127]
	v_mfma_f32_16x16x32_f16 v[116:119], v[150:153], v[198:201], v[116:119]
	v_mfma_f32_16x16x32_f16 v[108:111], v[158:161], v[198:201], v[108:111]
	v_mfma_f32_16x16x32_f16 v[100:103], v[150:153], v[206:209], v[100:103]
	v_mfma_f32_16x16x32_f16 v[92:95], v[158:161], v[206:209], v[92:95]
	v_mfma_f32_16x16x32_f16 v[84:87], v[150:153], v[214:217], v[84:87]
	v_mfma_f32_16x16x32_f16 v[76:79], v[158:161], v[214:217], v[76:79]
	v_mfma_f32_16x16x32_f16 v[128:131], v[154:157], v[194:197], v[128:131]
	v_mfma_f32_16x16x32_f16 v[124:127], v[162:165], v[194:197], v[124:127]
	v_mfma_f32_16x16x32_f16 v[116:119], v[154:157], v[202:205], v[116:119]
	v_mfma_f32_16x16x32_f16 v[108:111], v[162:165], v[202:205], v[108:111]
	v_mfma_f32_16x16x32_f16 v[100:103], v[154:157], v[210:213], v[100:103]
	v_mfma_f32_16x16x32_f16 v[92:95], v[162:165], v[210:213], v[92:95]
	v_mfma_f32_16x16x32_f16 v[84:87], v[154:157], v[218:221], v[84:87]
	v_mfma_f32_16x16x32_f16 v[76:79], v[162:165], v[218:221], v[76:79]
	v_mfma_f32_16x16x32_f16 v[120:123], v[166:169], v[190:193], v[120:123]
	v_mfma_f32_16x16x32_f16 v[112:115], v[174:177], v[190:193], v[112:115]
	v_mfma_f32_16x16x32_f16 v[104:107], v[166:169], v[198:201], v[104:107]
	v_mfma_f32_16x16x32_f16 v[96:99], v[174:177], v[198:201], v[96:99]
	v_mfma_f32_16x16x32_f16 v[88:91], v[166:169], v[206:209], v[88:91]
	v_mfma_f32_16x16x32_f16 v[80:83], v[174:177], v[206:209], v[80:83]
	v_mfma_f32_16x16x32_f16 v[72:75], v[166:169], v[214:217], v[72:75]
	v_mfma_f32_16x16x32_f16 v[68:71], v[174:177], v[214:217], v[68:71]
	v_mfma_f32_16x16x32_f16 v[120:123], v[170:173], v[194:197], v[120:123]
	v_mfma_f32_16x16x32_f16 v[112:115], v[178:181], v[194:197], v[112:115]
	v_mfma_f32_16x16x32_f16 v[104:107], v[170:173], v[202:205], v[104:107]
	v_mfma_f32_16x16x32_f16 v[96:99], v[178:181], v[202:205], v[96:99]
	v_mfma_f32_16x16x32_f16 v[88:91], v[170:173], v[210:213], v[88:91]
	v_mfma_f32_16x16x32_f16 v[80:83], v[178:181], v[210:213], v[80:83]
	v_mfma_f32_16x16x32_f16 v[72:75], v[170:173], v[218:221], v[72:75]
	v_mfma_f32_16x16x32_f16 v[68:71], v[178:181], v[218:221], v[68:71]
	s_barrier
	s_add_i32 s25, s25, s2
	v_lshl_add_u64 v[182:183], s[76:77], 0, v[2:3]
	s_mov_b32 m0, s25
	ds_read_b128 v[190:193], v149 offset:49152
	ds_read_b128 v[194:197], v149 offset:50176
	ds_read_b128 v[198:201], v149 offset:51200
	ds_read_b128 v[202:205], v149 offset:52224
	ds_read_b128 v[206:209], v149 offset:53248
	ds_read_b128 v[210:213], v149 offset:54272
	ds_read_b128 v[214:217], v149 offset:55296
	ds_read_b128 v[218:221], v149 offset:56320
	global_load_lds_dwordx4 v[182:183], off
	s_add_i32 m0, s25, 0x2000
	s_add_u32 s30, s76, 0x80000
	v_lshl_add_u64 v[182:183], s[76:77], 0, v[132:133]
	s_addc_u32 s31, s77, 0
	s_add_i32 s25, s27, s2
	global_load_lds_dwordx4 v[182:183], off
	v_lshl_add_u64 v[182:183], s[30:31], 0, v[2:3]
	s_mov_b32 m0, s25
	s_nop 0
	global_load_lds_dwordx4 v[182:183], off
	v_lshl_add_u64 v[182:183], s[30:31], 0, v[132:133]
	s_add_i32 m0, s25, 0x2000
	s_nop 0
	global_load_lds_dwordx4 v[182:183], off
	v_lshl_add_u64 v[182:183], s[74:75], 0, v[136:137]
	s_mov_b32 m0, s35
	s_nop 0
	global_load_lds_dwordx4 v[182:183], off
	v_lshl_add_u64 v[182:183], s[74:75], 0, v[134:135]
	s_mov_b32 m0, s59
	s_nop 0
	global_load_lds_dwordx4 v[182:183], off
	s_waitcnt vmcnt(8)
	s_waitcnt lgkmcnt(0)
	s_barrier
	v_mfma_f32_16x16x32_f16 v[64:67], v[150:153], v[190:193], v[64:67]
	v_mfma_f32_16x16x32_f16 v[60:63], v[158:161], v[190:193], v[60:63]
	v_mfma_f32_16x16x32_f16 v[52:55], v[150:153], v[198:201], v[52:55]
	v_mfma_f32_16x16x32_f16 v[44:47], v[158:161], v[198:201], v[44:47]
	v_mfma_f32_16x16x32_f16 v[36:39], v[150:153], v[206:209], v[36:39]
	v_mfma_f32_16x16x32_f16 v[28:31], v[158:161], v[206:209], v[28:31]
	v_mfma_f32_16x16x32_f16 v[20:23], v[150:153], v[214:217], v[20:23]
	v_mfma_f32_16x16x32_f16 v[12:15], v[158:161], v[214:217], v[12:15]
	v_mfma_f32_16x16x32_f16 v[64:67], v[154:157], v[194:197], v[64:67]
	v_mfma_f32_16x16x32_f16 v[60:63], v[162:165], v[194:197], v[60:63]
	v_mfma_f32_16x16x32_f16 v[52:55], v[154:157], v[202:205], v[52:55]
	v_mfma_f32_16x16x32_f16 v[44:47], v[162:165], v[202:205], v[44:47]
	v_mfma_f32_16x16x32_f16 v[36:39], v[154:157], v[210:213], v[36:39]
	v_mfma_f32_16x16x32_f16 v[28:31], v[162:165], v[210:213], v[28:31]
	v_mfma_f32_16x16x32_f16 v[20:23], v[154:157], v[218:221], v[20:23]
	v_mfma_f32_16x16x32_f16 v[12:15], v[162:165], v[218:221], v[12:15]
	v_mfma_f32_16x16x32_f16 v[56:59], v[166:169], v[190:193], v[56:59]
	v_mfma_f32_16x16x32_f16 v[48:51], v[174:177], v[190:193], v[48:51]
	v_mfma_f32_16x16x32_f16 v[40:43], v[166:169], v[198:201], v[40:43]
	v_mfma_f32_16x16x32_f16 v[32:35], v[174:177], v[198:201], v[32:35]
	v_mfma_f32_16x16x32_f16 v[24:27], v[166:169], v[206:209], v[24:27]
	v_mfma_f32_16x16x32_f16 v[16:19], v[174:177], v[206:209], v[16:19]
	v_mfma_f32_16x16x32_f16 v[8:11], v[166:169], v[214:217], v[8:11]
	v_mfma_f32_16x16x32_f16 v[4:7], v[174:177], v[214:217], v[4:7]
	v_mfma_f32_16x16x32_f16 v[56:59], v[170:173], v[194:197], v[56:59]
	v_mfma_f32_16x16x32_f16 v[48:51], v[178:181], v[194:197], v[48:51]
	v_mfma_f32_16x16x32_f16 v[40:43], v[170:173], v[202:205], v[40:43]
	v_mfma_f32_16x16x32_f16 v[32:35], v[178:181], v[202:205], v[32:35]
	v_mfma_f32_16x16x32_f16 v[24:27], v[170:173], v[210:213], v[24:27]
	v_mfma_f32_16x16x32_f16 v[16:19], v[178:181], v[210:213], v[16:19]
	v_mfma_f32_16x16x32_f16 v[8:11], v[170:173], v[218:221], v[8:11]
	v_mfma_f32_16x16x32_f16 v[4:7], v[178:181], v[218:221], v[4:7]
	s_barrier
	s_add_i32 s21, s21, 2
	s_add_u32 s72, s72, 0x100
	s_addc_u32 s73, s73, 0
	s_cmp_gt_u32 s21, 29
	s_cbranch_scc1 .LBB0_756

; #define G_STAGE(bufoff, gbase, voff) do { _Pragma("unroll") for (int _i = 0; _i < 2; ++_i) \
;         __builtin_amdgcn_global_load_lds((const unsigned*)((const char*)(gbase) + (voff)[_i]), (LAS unsigned*)(lds + (bufoff) + ldsw + _i * 8192), 16, 0, 0); } while (0)
; #define G_LDA(dst, b, h) do { _Pragma("unroll") for (int m = 0; m < 4; ++m) { const i32x4 _p0 = *(const LAS i32x4*)(lds + G_SA(b, h) + aoff + m * 2048), _p1 = *(const LAS i32x4*)(lds + G_SA(b, h) + aoff + m * 2048 + 1024); \
;         dst[m] = __builtin_shufflevector(_p0, _p1, 0, 1, 2, 3, 4, 5, 6, 7); } } while (0)
; #define G_LDB(dst, b, h) do { _Pragma("unroll") for (int n = 0; n < 2; ++n) { const i32x4 _p0 = *(const LAS i32x4*)(lds + G_SB(b, h) + boff + n * 2048), _p1 = *(const LAS i32x4*)(lds + G_SB(b, h) + boff + n * 2048 + 1024); \
;         dst[n] = __builtin_shufflevector(_p0, _p1, 0, 1, 2, 3, 4, 5, 6, 7); } } while (0)
; #define G_WAIT_V(n) asm volatile("s_waitcnt vmcnt(" #n ")" ::: "memory")
; #define G_WAIT_L(n) asm volatile("s_waitcnt lgkmcnt(" #n ")" ::: "memory")
; #define G_BAR __builtin_amdgcn_s_barrier()
; #define G_SCHED __builtin_amdgcn_sched_barrier(0)
; template <int NS, int MODE  , class Epi>
; __device__ __forceinline__ void gemm_phase(LAS unsigned char* lds, const Gemm g, const StaticOrder& S, const Epi& E) {
;     ...
;             G_LDB(B0, 0, 0); G_LDB(B1, 0, 1); G_SCHED; G_LDA(At, 0, 0); G_STAGE(G_SA(1, 1), a1 + hstep, voffA);
;             G_WAIT_V(8); G_WAIT_L(0); G_BAR; G_MMA(0, 0, At, B0); G_MMA(0, 1, At, B1); G_BAR; G_SCHED;
;             G_LDA(At, 0, 1); G_STAGE(G_SB(0, 0), b2, voffB); G_STAGE(G_SB(0, 1), b2 + hstep, voffB); G_STAGE(G_SA(0, 0), a2, voffA);
;             G_WAIT_V(8); G_WAIT_L(0); G_BAR; G_MMA(1, 0, At, B0); G_MMA(1, 1, At, B1); G_BAR; G_SCHED;
.LBB0_1126:
	s_add_i32 s21, 0, 0x10000
	s_add_i32 s30, 0, 0x14000
	v_add_u32_e32 v148, s21, v205
	v_add_u32_e32 v164, s30, v205
	ds_read_b128 v[136:139], v148
	ds_read_b128 v[140:143], v148 offset:1024
	ds_read_b128 v[144:147], v148 offset:2048
	ds_read_b128 v[148:151], v148 offset:3072
	ds_read_b128 v[152:155], v164
	ds_read_b128 v[156:159], v164 offset:1024
	ds_read_b128 v[160:163], v164 offset:2048
	ds_read_b128 v[164:167], v164 offset:3072
	v_lshl_add_u64 v[216:217], v[132:133], 0, s[60:61]
	s_add_i32 m0, s19, 0xc000
	ds_read_b128 v[176:179], v207
	ds_read_b128 v[180:183], v207 offset:1024
	ds_read_b128 v[188:191], v207 offset:2048
	ds_read_b128 v[192:195], v207 offset:3072
	ds_read_b128 v[196:199], v207 offset:4096
	ds_read_b128 v[200:203], v207 offset:5120
	ds_read_b128 v[208:211], v207 offset:6144
	ds_read_b128 v[212:215], v207 offset:7168
	global_load_lds_dwordx4 v[216:217], off
	v_lshl_add_u64 v[216:217], v[134:135], 0, s[60:61]
	s_add_i32 m0, s19, 0xe000
	s_nop 0
	global_load_lds_dwordx4 v[216:217], off
	s_waitcnt vmcnt(8)
	s_waitcnt lgkmcnt(0)
	s_barrier
	v_mfma_f32_16x16x32_f16 v[128:131], v[136:139], v[176:179], v[128:131]
	v_mfma_f32_16x16x32_f16 v[124:127], v[144:147], v[176:179], v[124:127]
	v_mfma_f32_16x16x32_f16 v[112:115], v[136:139], v[188:191], v[112:115]
	v_mfma_f32_16x16x32_f16 v[108:111], v[144:147], v[188:191], v[108:111]
	v_mfma_f32_16x16x32_f16 v[100:103], v[136:139], v[196:199], v[100:103]
	v_mfma_f32_16x16x32_f16 v[92:95], v[144:147], v[196:199], v[92:95]
	v_mfma_f32_16x16x32_f16 v[88:91], v[136:139], v[208:211], v[88:91]
	v_mfma_f32_16x16x32_f16 v[80:83], v[144:147], v[208:211], v[80:83]
	v_mfma_f32_16x16x32_f16 v[128:131], v[140:143], v[180:183], v[128:131]
	v_mfma_f32_16x16x32_f16 v[124:127], v[148:151], v[180:183], v[124:127]
	v_mfma_f32_16x16x32_f16 v[112:115], v[140:143], v[192:195], v[112:115]
	v_mfma_f32_16x16x32_f16 v[108:111], v[148:151], v[192:195], v[108:111]
	v_mfma_f32_16x16x32_f16 v[100:103], v[140:143], v[200:203], v[100:103]
	v_mfma_f32_16x16x32_f16 v[92:95], v[148:151], v[200:203], v[92:95]
	v_mfma_f32_16x16x32_f16 v[88:91], v[140:143], v[212:215], v[88:91]
	v_mfma_f32_16x16x32_f16 v[80:83], v[148:151], v[212:215], v[80:83]
	v_mfma_f32_16x16x32_f16 v[120:123], v[152:155], v[176:179], v[120:123]
	v_mfma_f32_16x16x32_f16 v[116:119], v[160:163], v[176:179], v[116:119]
	v_mfma_f32_16x16x32_f16 v[104:107], v[152:155], v[188:191], v[104:107]
	v_mfma_f32_16x16x32_f16 v[96:99], v[160:163], v[188:191], v[96:99]
	v_mfma_f32_16x16x32_f16 v[84:87], v[152:155], v[196:199], v[84:87]
	v_mfma_f32_16x16x32_f16 v[76:79], v[160:163], v[196:199], v[76:79]
	v_mfma_f32_16x16x32_f16 v[72:75], v[152:155], v[208:211], v[72:75]
	v_mfma_f32_16x16x32_f16 v[68:71], v[160:163], v[208:211], v[68:71]
	v_mfma_f32_16x16x32_f16 v[120:123], v[156:159], v[180:183], v[120:123]
	v_mfma_f32_16x16x32_f16 v[116:119], v[164:167], v[180:183], v[116:119]
	v_mfma_f32_16x16x32_f16 v[104:107], v[156:159], v[192:195], v[104:107]
	v_mfma_f32_16x16x32_f16 v[96:99], v[164:167], v[192:195], v[96:99]
	v_mfma_f32_16x16x32_f16 v[84:87], v[156:159], v[200:203], v[84:87]
	v_mfma_f32_16x16x32_f16 v[76:79], v[164:167], v[200:203], v[76:79]
	v_mfma_f32_16x16x32_f16 v[72:75], v[156:159], v[212:215], v[72:75]
	v_mfma_f32_16x16x32_f16 v[68:71], v[164:167], v[212:215], v[68:71]
	s_barrier
	s_add_i32 s21, s21, s18
	v_lshl_add_u64 v[216:217], s[68:69], 0, v[2:3]
	s_mov_b32 m0, s21
	ds_read_b128 v[176:179], v207 offset:16384
	ds_read_b128 v[180:183], v207 offset:17408
	ds_read_b128 v[188:191], v207 offset:18432
	ds_read_b128 v[192:195], v207 offset:19456
	ds_read_b128 v[196:199], v207 offset:20480
	ds_read_b128 v[200:203], v207 offset:21504
	ds_read_b128 v[208:211], v207 offset:22528
	ds_read_b128 v[212:215], v207 offset:23552
	global_load_lds_dwordx4 v[216:217], off
	s_add_i32 m0, s21, 0x2000
	s_add_u32 s24, s68, 0x80000
	v_lshl_add_u64 v[216:217], s[68:69], 0, v[168:169]
	s_addc_u32 s25, s69, 0
	s_add_i32 s21, s30, s18
	global_load_lds_dwordx4 v[216:217], off
	v_lshl_add_u64 v[216:217], s[24:25], 0, v[2:3]
	s_mov_b32 m0, s21
	s_nop 0
	global_load_lds_dwordx4 v[216:217], off
	v_lshl_add_u64 v[216:217], s[24:25], 0, v[168:169]
	s_add_i32 m0, s21, 0x2000
	s_nop 0
	global_load_lds_dwordx4 v[216:217], off
	v_lshl_add_u64 v[216:217], s[66:67], 0, v[172:173]
	s_mov_b32 m0, s19
	s_nop 0
	global_load_lds_dwordx4 v[216:217], off
	v_lshl_add_u64 v[216:217], s[66:67], 0, v[170:171]
	s_mov_b32 m0, s29
	s_nop 0
	global_load_lds_dwordx4 v[216:217], off
	s_waitcnt vmcnt(8)
	s_waitcnt lgkmcnt(0)
	s_barrier
; #define G_STAGE(bufoff, gbase, voff) do { _Pragma("unroll") for (int _i = 0; _i < 2; ++_i) \
;         __builtin_amdgcn_global_load_lds((const unsigned*)((const char*)(gbase) + (voff)[_i]), (LAS unsigned*)(lds + (bufoff) + ldsw + _i * 8192), 16, 0, 0); } while (0)
; #define G_LDA(dst, b, h) do { _Pragma("unroll") for (int m = 0; m < 4; ++m) { const i32x4 _p0 = *(const LAS i32x4*)(lds + G_SA(b, h) + aoff + m * 2048), _p1 = *(const LAS i32x4*)(lds + G_SA(b, h) + aoff + m * 2048 + 1024); \
;         dst[m] = __builtin_shufflevector(_p0, _p1, 0, 1, 2, 3, 4, 5, 6, 7); } } while (0)
; #define G_LDB(dst, b, h) do { _Pragma("unroll") for (int n = 0; n < 2; ++n) { const i32x4 _p0 = *(const LAS i32x4*)(lds + G_SB(b, h) + boff + n * 2048), _p1 = *(const LAS i32x4*)(lds + G_SB(b, h) + boff + n * 2048 + 1024); \
;         dst[n] = __builtin_shufflevector(_p0, _p1, 0, 1, 2, 3, 4, 5, 6, 7); } } while (0)
; #define G_WAIT_V(n) asm volatile("s_waitcnt vmcnt(" #n ")" ::: "memory")
; #define G_WAIT_L(n) asm volatile("s_waitcnt lgkmcnt(" #n ")" ::: "memory")
; #define G_BAR __builtin_amdgcn_s_barrier()
; #define G_SCHED __builtin_amdgcn_sched_barrier(0)
; template <int NS, int MODE  , class Epi>
; __device__ __forceinline__ void gemm_phase(LAS unsigned char* lds, const Gemm g, const StaticOrder& S, const Epi& E) {
;     ...
;             G_WAIT_V(8); G_WAIT_L(0); G_BAR; G_MMA(1, 0, At, B0); G_MMA(1, 1, At, B1); G_BAR; G_SCHED;
;             G_LDB(B0, 1, 0); G_LDB(B1, 1, 1); G_SCHED; G_LDA(At, 1, 0); G_STAGE(G_SA(0, 1), a2 + hstep, voffA);
;             G_WAIT_V(8); G_WAIT_L(0); G_BAR; G_MMA(0, 0, At, B0); G_MMA(0, 1, At, B1); G_BAR; G_SCHED;
	v_mfma_f32_16x16x32_f16 v[64:67], v[136:139], v[176:179], v[64:67]
	v_mfma_f32_16x16x32_f16 v[60:63], v[144:147], v[176:179], v[60:63]
	v_mfma_f32_16x16x32_f16 v[52:55], v[136:139], v[188:191], v[52:55]
	v_mfma_f32_16x16x32_f16 v[44:47], v[144:147], v[188:191], v[44:47]
	v_mfma_f32_16x16x32_f16 v[36:39], v[136:139], v[196:199], v[36:39]
	v_mfma_f32_16x16x32_f16 v[28:31], v[144:147], v[196:199], v[28:31]
	v_mfma_f32_16x16x32_f16 v[20:23], v[136:139], v[208:211], v[20:23]
	v_mfma_f32_16x16x32_f16 v[12:15], v[144:147], v[208:211], v[12:15]
	v_mfma_f32_16x16x32_f16 v[64:67], v[140:143], v[180:183], v[64:67]
	v_mfma_f32_16x16x32_f16 v[60:63], v[148:151], v[180:183], v[60:63]
	v_mfma_f32_16x16x32_f16 v[52:55], v[140:143], v[192:195], v[52:55]
	v_mfma_f32_16x16x32_f16 v[44:47], v[148:151], v[192:195], v[44:47]
	v_mfma_f32_16x16x32_f16 v[36:39], v[140:143], v[200:203], v[36:39]
	v_mfma_f32_16x16x32_f16 v[28:31], v[148:151], v[200:203], v[28:31]
	v_mfma_f32_16x16x32_f16 v[20:23], v[140:143], v[212:215], v[20:23]
	v_mfma_f32_16x16x32_f16 v[12:15], v[148:151], v[212:215], v[12:15]
	v_mfma_f32_16x16x32_f16 v[56:59], v[152:155], v[176:179], v[56:59]
	v_mfma_f32_16x16x32_f16 v[48:51], v[160:163], v[176:179], v[48:51]
	v_mfma_f32_16x16x32_f16 v[40:43], v[152:155], v[188:191], v[40:43]
	v_mfma_f32_16x16x32_f16 v[32:35], v[160:163], v[188:191], v[32:35]
	v_mfma_f32_16x16x32_f16 v[24:27], v[152:155], v[196:199], v[24:27]
	v_mfma_f32_16x16x32_f16 v[16:19], v[160:163], v[196:199], v[16:19]
	v_mfma_f32_16x16x32_f16 v[8:11], v[152:155], v[208:211], v[8:11]
	v_mfma_f32_16x16x32_f16 v[4:7], v[160:163], v[208:211], v[4:7]
	v_mfma_f32_16x16x32_f16 v[56:59], v[156:159], v[180:183], v[56:59]
	v_mfma_f32_16x16x32_f16 v[48:51], v[164:167], v[180:183], v[48:51]
	v_mfma_f32_16x16x32_f16 v[40:43], v[156:159], v[192:195], v[40:43]
	v_mfma_f32_16x16x32_f16 v[32:35], v[164:167], v[192:195], v[32:35]
	v_mfma_f32_16x16x32_f16 v[24:27], v[156:159], v[200:203], v[24:27]
	v_mfma_f32_16x16x32_f16 v[16:19], v[164:167], v[200:203], v[16:19]
	v_mfma_f32_16x16x32_f16 v[8:11], v[156:159], v[212:215], v[8:11]
	v_mfma_f32_16x16x32_f16 v[4:7], v[164:167], v[212:215], v[4:7]
	s_barrier
	s_add_i32 s21, 0, 0x18000
	s_add_i32 s30, 0, 0x1c000
	v_add_u32_e32 v148, s21, v205
	v_add_u32_e32 v164, s30, v205
	ds_read_b128 v[136:139], v148
	ds_read_b128 v[140:143], v148 offset:1024
	ds_read_b128 v[144:147], v148 offset:2048
	ds_read_b128 v[148:151], v148 offset:3072
	ds_read_b128 v[152:155], v164
	ds_read_b128 v[156:159], v164 offset:1024
	ds_read_b128 v[160:163], v164 offset:2048
	ds_read_b128 v[164:167], v164 offset:3072
	s_add_u32 s24, s66, 0x80000
	s_addc_u32 s25, s67, 0
	s_mov_b32 m0, s56
	v_lshl_add_u64 v[216:217], s[24:25], 0, v[172:173]
	ds_read_b128 v[176:179], v207 offset:32768
	ds_read_b128 v[180:183], v207 offset:33792
	ds_read_b128 v[188:191], v207 offset:34816
	ds_read_b128 v[192:195], v207 offset:35840
	ds_read_b128 v[196:199], v207 offset:36864
	ds_read_b128 v[200:203], v207 offset:37888
	ds_read_b128 v[208:211], v207 offset:38912
	ds_read_b128 v[212:215], v207 offset:39936
	global_load_lds_dwordx4 v[216:217], off
	v_lshl_add_u64 v[216:217], s[24:25], 0, v[170:171]
	s_mov_b32 m0, s70
	s_nop 0
	global_load_lds_dwordx4 v[216:217], off
	s_waitcnt vmcnt(8)
	s_waitcnt lgkmcnt(0)
	s_barrier
	v_mfma_f32_16x16x32_f16 v[128:131], v[136:139], v[176:179], v[128:131]
	v_mfma_f32_16x16x32_f16 v[124:127], v[144:147], v[176:179], v[124:127]
	v_mfma_f32_16x16x32_f16 v[112:115], v[136:139], v[188:191], v[112:115]
	v_mfma_f32_16x16x32_f16 v[108:111], v[144:147], v[188:191], v[108:111]
	v_mfma_f32_16x16x32_f16 v[100:103], v[136:139], v[196:199], v[100:103]
	v_mfma_f32_16x16x32_f16 v[92:95], v[144:147], v[196:199], v[92:95]
	v_mfma_f32_16x16x32_f16 v[88:91], v[136:139], v[208:211], v[88:91]
	v_mfma_f32_16x16x32_f16 v[80:83], v[144:147], v[208:211], v[80:83]
	v_mfma_f32_16x16x32_f16 v[128:131], v[140:143], v[180:183], v[128:131]
	v_mfma_f32_16x16x32_f16 v[124:127], v[148:151], v[180:183], v[124:127]
	v_mfma_f32_16x16x32_f16 v[112:115], v[140:143], v[192:195], v[112:115]
	v_mfma_f32_16x16x32_f16 v[108:111], v[148:151], v[192:195], v[108:111]
	v_mfma_f32_16x16x32_f16 v[100:103], v[140:143], v[200:203], v[100:103]
	v_mfma_f32_16x16x32_f16 v[92:95], v[148:151], v[200:203], v[92:95]
	v_mfma_f32_16x16x32_f16 v[88:91], v[140:143], v[212:215], v[88:91]
	v_mfma_f32_16x16x32_f16 v[80:83], v[148:151], v[212:215], v[80:83]
	v_mfma_f32_16x16x32_f16 v[120:123], v[152:155], v[176:179], v[120:123]
	v_mfma_f32_16x16x32_f16 v[116:119], v[160:163], v[176:179], v[116:119]
	v_mfma_f32_16x16x32_f16 v[104:107], v[152:155], v[188:191], v[104:107]
	v_mfma_f32_16x16x32_f16 v[96:99], v[160:163], v[188:191], v[96:99]
	v_mfma_f32_16x16x32_f16 v[84:87], v[152:155], v[196:199], v[84:87]
	v_mfma_f32_16x16x32_f16 v[76:79], v[160:163], v[196:199], v[76:79]
	v_mfma_f32_16x16x32_f16 v[72:75], v[152:155], v[208:211], v[72:75]
	v_mfma_f32_16x16x32_f16 v[68:71], v[160:163], v[208:211], v[68:71]
	v_mfma_f32_16x16x32_f16 v[120:123], v[156:159], v[180:183], v[120:123]
	v_mfma_f32_16x16x32_f16 v[116:119], v[164:167], v[180:183], v[116:119]
	v_mfma_f32_16x16x32_f16 v[104:107], v[156:159], v[192:195], v[104:107]
	v_mfma_f32_16x16x32_f16 v[96:99], v[164:167], v[192:195], v[96:99]
	v_mfma_f32_16x16x32_f16 v[84:87], v[156:159], v[200:203], v[84:87]
	v_mfma_f32_16x16x32_f16 v[76:79], v[164:167], v[200:203], v[76:79]
	v_mfma_f32_16x16x32_f16 v[72:75], v[156:159], v[212:215], v[72:75]
	v_mfma_f32_16x16x32_f16 v[68:71], v[164:167], v[212:215], v[68:71]
	s_barrier
; #define G_STAGE(bufoff, gbase, voff) do { _Pragma("unroll") for (int _i = 0; _i < 2; ++_i) \
;         __builtin_amdgcn_global_load_lds((const unsigned*)((const char*)(gbase) + (voff)[_i]), (LAS unsigned*)(lds + (bufoff) + ldsw + _i * 8192), 16, 0, 0); } while (0)
; #define G_LDA(dst, b, h) do { _Pragma("unroll") for (int m = 0; m < 4; ++m) { const i32x4 _p0 = *(const LAS i32x4*)(lds + G_SA(b, h) + aoff + m * 2048), _p1 = *(const LAS i32x4*)(lds + G_SA(b, h) + aoff + m * 2048 + 1024); \
;         dst[m] = __builtin_shufflevector(_p0, _p1, 0, 1, 2, 3, 4, 5, 6, 7); } } while (0)
; #define G_WAIT_V(n) asm volatile("s_waitcnt vmcnt(" #n ")" ::: "memory")
; #define G_WAIT_L(n) asm volatile("s_waitcnt lgkmcnt(" #n ")" ::: "memory")
; #define G_BAR __builtin_amdgcn_s_barrier()
; #define G_SCHED __builtin_amdgcn_sched_barrier(0)
; template <int NS, int MODE  , class Epi>
; __device__ __forceinline__ void gemm_phase(LAS unsigned char* lds, const Gemm g, const StaticOrder& S, const Epi& E) {
;     ...
;             G_LDA(At, 1, 1); G_STAGE(G_SB(1, 0), b3, voffB); G_STAGE(G_SB(1, 1), b3 + hstep, voffB); G_STAGE(G_SA(1, 0), a3, voffA);
;             G_WAIT_V(8); G_WAIT_L(0); G_BAR; G_MMA(1, 0, At, B0); G_MMA(1, 1, At, B1); G_BAR; G_SCHED;
	s_add_i32 s21, s21, s18
	v_lshl_add_u64 v[216:217], s[64:65], 0, v[2:3]
	s_mov_b32 m0, s21
	ds_read_b128 v[176:179], v207 offset:49152
	ds_read_b128 v[180:183], v207 offset:50176
	ds_read_b128 v[188:191], v207 offset:51200
	ds_read_b128 v[192:195], v207 offset:52224
	ds_read_b128 v[196:199], v207 offset:53248
	ds_read_b128 v[200:203], v207 offset:54272
	ds_read_b128 v[208:211], v207 offset:55296
	ds_read_b128 v[212:215], v207 offset:56320
	global_load_lds_dwordx4 v[216:217], off
	s_add_i32 m0, s21, 0x2000
	s_add_u32 s24, s64, 0x80000
	v_lshl_add_u64 v[216:217], s[64:65], 0, v[168:169]
	s_addc_u32 s25, s65, 0
	s_add_i32 s21, s30, s18
	global_load_lds_dwordx4 v[216:217], off
	v_lshl_add_u64 v[216:217], s[24:25], 0, v[2:3]
	s_mov_b32 m0, s21
	s_nop 0
	global_load_lds_dwordx4 v[216:217], off
	v_lshl_add_u64 v[216:217], s[24:25], 0, v[168:169]
	s_add_i32 m0, s21, 0x2000
	s_nop 0
	global_load_lds_dwordx4 v[216:217], off
	v_lshl_add_u64 v[216:217], s[62:63], 0, v[172:173]
	s_mov_b32 m0, s73
	s_nop 0
	global_load_lds_dwordx4 v[216:217], off
	v_lshl_add_u64 v[216:217], s[62:63], 0, v[170:171]
	s_mov_b32 m0, s74
	s_nop 0
	global_load_lds_dwordx4 v[216:217], off
	s_waitcnt vmcnt(8)
	s_waitcnt lgkmcnt(0)
	s_barrier
	v_mfma_f32_16x16x32_f16 v[64:67], v[136:139], v[176:179], v[64:67]
	v_mfma_f32_16x16x32_f16 v[60:63], v[144:147], v[176:179], v[60:63]
	v_mfma_f32_16x16x32_f16 v[52:55], v[136:139], v[188:191], v[52:55]
	v_mfma_f32_16x16x32_f16 v[44:47], v[144:147], v[188:191], v[44:47]
	v_mfma_f32_16x16x32_f16 v[36:39], v[136:139], v[196:199], v[36:39]
	v_mfma_f32_16x16x32_f16 v[28:31], v[144:147], v[196:199], v[28:31]
	v_mfma_f32_16x16x32_f16 v[20:23], v[136:139], v[208:211], v[20:23]
	v_mfma_f32_16x16x32_f16 v[12:15], v[144:147], v[208:211], v[12:15]
	v_mfma_f32_16x16x32_f16 v[64:67], v[140:143], v[180:183], v[64:67]
	v_mfma_f32_16x16x32_f16 v[60:63], v[148:151], v[180:183], v[60:63]
	v_mfma_f32_16x16x32_f16 v[52:55], v[140:143], v[192:195], v[52:55]
	v_mfma_f32_16x16x32_f16 v[44:47], v[148:151], v[192:195], v[44:47]
	v_mfma_f32_16x16x32_f16 v[36:39], v[140:143], v[200:203], v[36:39]
	v_mfma_f32_16x16x32_f16 v[28:31], v[148:151], v[200:203], v[28:31]
	v_mfma_f32_16x16x32_f16 v[20:23], v[140:143], v[212:215], v[20:23]
	v_mfma_f32_16x16x32_f16 v[12:15], v[148:151], v[212:215], v[12:15]
	v_mfma_f32_16x16x32_f16 v[56:59], v[152:155], v[176:179], v[56:59]
	v_mfma_f32_16x16x32_f16 v[48:51], v[160:163], v[176:179], v[48:51]
	v_mfma_f32_16x16x32_f16 v[40:43], v[152:155], v[188:191], v[40:43]
	v_mfma_f32_16x16x32_f16 v[32:35], v[160:163], v[188:191], v[32:35]
	v_mfma_f32_16x16x32_f16 v[24:27], v[152:155], v[196:199], v[24:27]
	v_mfma_f32_16x16x32_f16 v[16:19], v[160:163], v[196:199], v[16:19]
	v_mfma_f32_16x16x32_f16 v[8:11], v[152:155], v[208:211], v[8:11]
	v_mfma_f32_16x16x32_f16 v[4:7], v[160:163], v[208:211], v[4:7]
	v_mfma_f32_16x16x32_f16 v[56:59], v[156:159], v[180:183], v[56:59]
	v_mfma_f32_16x16x32_f16 v[48:51], v[164:167], v[180:183], v[48:51]
	v_mfma_f32_16x16x32_f16 v[40:43], v[156:159], v[192:195], v[40:43]
	v_mfma_f32_16x16x32_f16 v[32:35], v[164:167], v[192:195], v[32:35]
	v_mfma_f32_16x16x32_f16 v[24:27], v[156:159], v[200:203], v[24:27]
	v_mfma_f32_16x16x32_f16 v[16:19], v[164:167], v[200:203], v[16:19]
	v_mfma_f32_16x16x32_f16 v[8:11], v[156:159], v[212:215], v[8:11]
	v_mfma_f32_16x16x32_f16 v[4:7], v[164:167], v[212:215], v[4:7]
	s_barrier
	s_add_u32 s60, s60, 0x100
	s_addc_u32 s61, s61, 0
	s_add_i32 s13, s13, 2
	s_cmp_gt_u32 s13, 29
	s_cbranch_scc1 .LBB0_1129

; #define G_STAGE(bufoff, gbase, voff) do { _Pragma("unroll") for (int _i = 0; _i < 2; ++_i) \
;         __builtin_amdgcn_global_load_lds((const unsigned*)((const char*)(gbase) + (voff)[_i]), (LAS unsigned*)(lds + (bufoff) + ldsw + _i * 8192), 16, 0, 0); } while (0)
; #define G_LDA(dst, b, h) do { _Pragma("unroll") for (int m = 0; m < 4; ++m) { const i32x4 _p0 = *(const LAS i32x4*)(lds + G_SA(b, h) + aoff + m * 2048), _p1 = *(const LAS i32x4*)(lds + G_SA(b, h) + aoff + m * 2048 + 1024); \
;         dst[m] = __builtin_shufflevector(_p0, _p1, 0, 1, 2, 3, 4, 5, 6, 7); } } while (0)
; #define G_LDB(dst, b, h) do { _Pragma("unroll") for (int n = 0; n < 2; ++n) { const i32x4 _p0 = *(const LAS i32x4*)(lds + G_SB(b, h) + boff + n * 2048), _p1 = *(const LAS i32x4*)(lds + G_SB(b, h) + boff + n * 2048 + 1024); \
;         dst[n] = __builtin_shufflevector(_p0, _p1, 0, 1, 2, 3, 4, 5, 6, 7); } } while (0)
; #define G_WAIT_V(n) asm volatile("s_waitcnt vmcnt(" #n ")" ::: "memory")
; #define G_WAIT_L(n) asm volatile("s_waitcnt lgkmcnt(" #n ")" ::: "memory")
; #define G_BAR __builtin_amdgcn_s_barrier()
; #define G_SCHED __builtin_amdgcn_sched_barrier(0)
; template <int NS, int MODE  , class Epi>
; __device__ __forceinline__ void gemm_phase(LAS unsigned char* lds, const Gemm g, const StaticOrder& S, const Epi& E) {
;     ...
;             G_LDB(B0, 0, 0); G_LDB(B1, 0, 1); G_SCHED; G_LDA(At, 0, 0); G_STAGE(G_SA(1, 1), a1 + hstep, voffA);
;             G_WAIT_V(8); G_WAIT_L(0); G_BAR; G_MMA(0, 0, At, B0); G_MMA(0, 1, At, B1); G_BAR; G_SCHED;
;             G_LDA(At, 0, 1); G_STAGE(G_SB(0, 0), b2, voffB); G_STAGE(G_SB(0, 1), b2 + hstep, voffB); G_STAGE(G_SA(0, 0), a2, voffA);
;             G_WAIT_V(8); G_WAIT_L(0); G_BAR; G_MMA(1, 0, At, B0); G_MMA(1, 1, At, B1); G_BAR; G_SCHED;
.LBB0_1276:
	s_add_i32 s21, 0, 0x10000
	s_add_i32 s30, 0, 0x14000
	v_add_u32_e32 v132, s21, v190
	v_add_u32_e32 v136, s30, v190
	ds_read_b128 v[160:163], v132
	ds_read_b128 v[148:151], v132 offset:1024
	ds_read_b128 v[156:159], v132 offset:2048
	ds_read_b128 v[152:155], v132 offset:3072
	ds_read_b128 v[144:147], v136
	ds_read_b128 v[132:135], v136 offset:1024
	ds_read_b128 v[140:143], v136 offset:2048
	ds_read_b128 v[136:139], v136 offset:3072
	v_lshl_add_u64 v[226:227], v[174:175], 0, s[60:61]
	s_add_i32 m0, s19, 0xc000
	ds_read_b128 v[176:179], v194
	ds_read_b128 v[180:183], v194 offset:1024
	ds_read_b128 v[202:205], v194 offset:2048
	ds_read_b128 v[206:209], v194 offset:3072
	ds_read_b128 v[210:213], v194 offset:4096
	ds_read_b128 v[214:217], v194 offset:5120
	ds_read_b128 v[218:221], v194 offset:6144
	ds_read_b128 v[222:225], v194 offset:7168
	global_load_lds_dwordx4 v[226:227], off
	v_lshl_add_u64 v[226:227], v[186:187], 0, s[60:61]
	s_add_i32 m0, s19, 0xe000
	s_nop 0
	global_load_lds_dwordx4 v[226:227], off
	s_waitcnt vmcnt(8)
	s_waitcnt lgkmcnt(0)
	s_barrier
	v_mfma_i32_16x16x64_i8 v[128:131], v[160:163], v[176:179], v[128:131]
	v_mfma_i32_16x16x64_i8 v[120:123], v[156:159], v[176:179], v[120:123]
	v_mfma_i32_16x16x64_i8 v[112:115], v[160:163], v[202:205], v[112:115]
	v_mfma_i32_16x16x64_i8 v[104:107], v[156:159], v[202:205], v[104:107]
	v_mfma_i32_16x16x64_i8 v[96:99], v[160:163], v[210:213], v[96:99]
	v_mfma_i32_16x16x64_i8 v[88:91], v[156:159], v[210:213], v[88:91]
	v_mfma_i32_16x16x64_i8 v[80:83], v[160:163], v[218:221], v[80:83]
	v_mfma_i32_16x16x64_i8 v[72:75], v[156:159], v[218:221], v[72:75]
	s_nop 0
	v_mfma_i32_16x16x64_i8 v[128:131], v[148:151], v[180:183], v[128:131]
	v_mfma_i32_16x16x64_i8 v[120:123], v[152:155], v[180:183], v[120:123]
	v_mfma_i32_16x16x64_i8 v[112:115], v[148:151], v[206:209], v[112:115]
	v_mfma_i32_16x16x64_i8 v[104:107], v[152:155], v[206:209], v[104:107]
	v_mfma_i32_16x16x64_i8 v[96:99], v[148:151], v[214:217], v[96:99]
	v_mfma_i32_16x16x64_i8 v[88:91], v[152:155], v[214:217], v[88:91]
	v_mfma_i32_16x16x64_i8 v[80:83], v[148:151], v[222:225], v[80:83]
	v_mfma_i32_16x16x64_i8 v[72:75], v[152:155], v[222:225], v[72:75]
	v_mfma_i32_16x16x64_i8 v[124:127], v[144:147], v[176:179], v[124:127]
	v_mfma_i32_16x16x64_i8 v[116:119], v[140:143], v[176:179], v[116:119]
	v_mfma_i32_16x16x64_i8 v[108:111], v[144:147], v[202:205], v[108:111]
	v_mfma_i32_16x16x64_i8 v[100:103], v[140:143], v[202:205], v[100:103]
	v_mfma_i32_16x16x64_i8 v[92:95], v[144:147], v[210:213], v[92:95]
	v_mfma_i32_16x16x64_i8 v[84:87], v[140:143], v[210:213], v[84:87]
	v_mfma_i32_16x16x64_i8 v[76:79], v[144:147], v[218:221], v[76:79]
	v_mfma_i32_16x16x64_i8 v[68:71], v[140:143], v[218:221], v[68:71]
	s_nop 0
	v_mfma_i32_16x16x64_i8 v[124:127], v[132:135], v[180:183], v[124:127]
	v_mfma_i32_16x16x64_i8 v[116:119], v[136:139], v[180:183], v[116:119]
	v_mfma_i32_16x16x64_i8 v[108:111], v[132:135], v[206:209], v[108:111]
	v_mfma_i32_16x16x64_i8 v[100:103], v[136:139], v[206:209], v[100:103]
	v_mfma_i32_16x16x64_i8 v[92:95], v[132:135], v[214:217], v[92:95]
	v_mfma_i32_16x16x64_i8 v[84:87], v[136:139], v[214:217], v[84:87]
	v_mfma_i32_16x16x64_i8 v[76:79], v[132:135], v[222:225], v[76:79]
	v_mfma_i32_16x16x64_i8 v[68:71], v[136:139], v[222:225], v[68:71]
	s_barrier
	s_add_i32 s21, s21, s18
	v_lshl_add_u64 v[226:227], s[68:69], 0, v[2:3]
	s_mov_b32 m0, s21
	ds_read_b128 v[176:179], v194 offset:16384
	ds_read_b128 v[180:183], v194 offset:17408
	ds_read_b128 v[202:205], v194 offset:18432
	ds_read_b128 v[206:209], v194 offset:19456
	ds_read_b128 v[210:213], v194 offset:20480
	ds_read_b128 v[214:217], v194 offset:21504
	ds_read_b128 v[218:221], v194 offset:22528
	ds_read_b128 v[222:225], v194 offset:23552
	global_load_lds_dwordx4 v[226:227], off
	s_add_i32 m0, s21, 0x2000
	s_add_u32 s24, s68, 0x40000
	v_lshl_add_u64 v[226:227], s[68:69], 0, v[164:165]
	s_addc_u32 s25, s69, 0
	s_add_i32 s21, s30, s18
	global_load_lds_dwordx4 v[226:227], off
	v_lshl_add_u64 v[226:227], s[24:25], 0, v[2:3]
	s_mov_b32 m0, s21
	s_nop 0
	global_load_lds_dwordx4 v[226:227], off
	v_lshl_add_u64 v[226:227], s[24:25], 0, v[164:165]
	s_add_i32 m0, s21, 0x2000
	s_nop 0
	global_load_lds_dwordx4 v[226:227], off
	v_lshl_add_u64 v[226:227], s[66:67], 0, v[168:169]
	s_mov_b32 m0, s19
	s_nop 0
	global_load_lds_dwordx4 v[226:227], off
	v_lshl_add_u64 v[226:227], s[66:67], 0, v[166:167]
	s_mov_b32 m0, s29
	s_nop 0
	global_load_lds_dwordx4 v[226:227], off
	s_waitcnt vmcnt(8)
	s_waitcnt lgkmcnt(0)
	s_barrier
	v_mfma_i32_16x16x64_i8 v[64:67], v[160:163], v[176:179], v[64:67]
	v_mfma_i32_16x16x64_i8 v[56:59], v[156:159], v[176:179], v[56:59]
	v_mfma_i32_16x16x64_i8 v[48:51], v[160:163], v[202:205], v[48:51]
	v_mfma_i32_16x16x64_i8 v[40:43], v[156:159], v[202:205], v[40:43]
	v_mfma_i32_16x16x64_i8 v[32:35], v[160:163], v[210:213], v[32:35]
	v_mfma_i32_16x16x64_i8 v[24:27], v[156:159], v[210:213], v[24:27]
	v_mfma_i32_16x16x64_i8 v[16:19], v[160:163], v[218:221], v[16:19]
	v_mfma_i32_16x16x64_i8 v[8:11], v[156:159], v[218:221], v[8:11]
	s_nop 0
	v_mfma_i32_16x16x64_i8 v[64:67], v[148:151], v[180:183], v[64:67]
	v_mfma_i32_16x16x64_i8 v[56:59], v[152:155], v[180:183], v[56:59]
	v_mfma_i32_16x16x64_i8 v[48:51], v[148:151], v[206:209], v[48:51]
	v_mfma_i32_16x16x64_i8 v[40:43], v[152:155], v[206:209], v[40:43]
	v_mfma_i32_16x16x64_i8 v[32:35], v[148:151], v[214:217], v[32:35]
	v_mfma_i32_16x16x64_i8 v[24:27], v[152:155], v[214:217], v[24:27]
	v_mfma_i32_16x16x64_i8 v[16:19], v[148:151], v[222:225], v[16:19]
	v_mfma_i32_16x16x64_i8 v[8:11], v[152:155], v[222:225], v[8:11]
	v_mfma_i32_16x16x64_i8 v[60:63], v[144:147], v[176:179], v[60:63]
	v_mfma_i32_16x16x64_i8 v[52:55], v[140:143], v[176:179], v[52:55]
	v_mfma_i32_16x16x64_i8 v[44:47], v[144:147], v[202:205], v[44:47]
	v_mfma_i32_16x16x64_i8 v[36:39], v[140:143], v[202:205], v[36:39]
	v_mfma_i32_16x16x64_i8 v[28:31], v[144:147], v[210:213], v[28:31]
	v_mfma_i32_16x16x64_i8 v[20:23], v[140:143], v[210:213], v[20:23]
	v_mfma_i32_16x16x64_i8 v[12:15], v[144:147], v[218:221], v[12:15]
	v_mfma_i32_16x16x64_i8 v[4:7], v[140:143], v[218:221], v[4:7]
	s_nop 0
	v_mfma_i32_16x16x64_i8 v[60:63], v[132:135], v[180:183], v[60:63]
	v_mfma_i32_16x16x64_i8 v[52:55], v[136:139], v[180:183], v[52:55]
	v_mfma_i32_16x16x64_i8 v[44:47], v[132:135], v[206:209], v[44:47]
	v_mfma_i32_16x16x64_i8 v[36:39], v[136:139], v[206:209], v[36:39]
	v_mfma_i32_16x16x64_i8 v[28:31], v[132:135], v[214:217], v[28:31]
	v_mfma_i32_16x16x64_i8 v[20:23], v[136:139], v[214:217], v[20:23]
	v_mfma_i32_16x16x64_i8 v[12:15], v[132:135], v[222:225], v[12:15]
	v_mfma_i32_16x16x64_i8 v[4:7], v[136:139], v[222:225], v[4:7]
	s_barrier
; #define G_STAGE(bufoff, gbase, voff) do { _Pragma("unroll") for (int _i = 0; _i < 2; ++_i) \
;         __builtin_amdgcn_global_load_lds((const unsigned*)((const char*)(gbase) + (voff)[_i]), (LAS unsigned*)(lds + (bufoff) + ldsw + _i * 8192), 16, 0, 0); } while (0)
; #define G_LDA(dst, b, h) do { _Pragma("unroll") for (int m = 0; m < 4; ++m) { const i32x4 _p0 = *(const LAS i32x4*)(lds + G_SA(b, h) + aoff + m * 2048), _p1 = *(const LAS i32x4*)(lds + G_SA(b, h) + aoff + m * 2048 + 1024); \
;         dst[m] = __builtin_shufflevector(_p0, _p1, 0, 1, 2, 3, 4, 5, 6, 7); } } while (0)
; #define G_LDB(dst, b, h) do { _Pragma("unroll") for (int n = 0; n < 2; ++n) { const i32x4 _p0 = *(const LAS i32x4*)(lds + G_SB(b, h) + boff + n * 2048), _p1 = *(const LAS i32x4*)(lds + G_SB(b, h) + boff + n * 2048 + 1024); \
;         dst[n] = __builtin_shufflevector(_p0, _p1, 0, 1, 2, 3, 4, 5, 6, 7); } } while (0)
; #define G_WAIT_V(n) asm volatile("s_waitcnt vmcnt(" #n ")" ::: "memory")
; #define G_WAIT_L(n) asm volatile("s_waitcnt lgkmcnt(" #n ")" ::: "memory")
; #define G_BAR __builtin_amdgcn_s_barrier()
; #define G_SCHED __builtin_amdgcn_sched_barrier(0)
; template <int NS, int MODE  , class Epi>
; __device__ __forceinline__ void gemm_phase(LAS unsigned char* lds, const Gemm g, const StaticOrder& S, const Epi& E) {
;     ...
;             G_LDB(B0, 1, 0); G_LDB(B1, 1, 1); G_SCHED; G_LDA(At, 1, 0); G_STAGE(G_SA(0, 1), a2 + hstep, voffA);
;             G_WAIT_V(8); G_WAIT_L(0); G_BAR; G_MMA(0, 0, At, B0); G_MMA(0, 1, At, B1); G_BAR; G_SCHED;
;             G_LDA(At, 1, 1); G_STAGE(G_SB(1, 0), b3, voffB); G_STAGE(G_SB(1, 1), b3 + hstep, voffB); G_STAGE(G_SA(1, 0), a3, voffA);
;             G_WAIT_V(8); G_WAIT_L(0); G_BAR; G_MMA(1, 0, At, B0); G_MMA(1, 1, At, B1); G_BAR; G_SCHED;
	s_add_i32 s21, 0, 0x18000
	s_add_i32 s30, 0, 0x1c000
	v_add_u32_e32 v144, s21, v190
	v_add_u32_e32 v160, s30, v190
	ds_read_b128 v[132:135], v144
	ds_read_b128 v[136:139], v144 offset:1024
	ds_read_b128 v[140:143], v144 offset:2048
	ds_read_b128 v[144:147], v144 offset:3072
	ds_read_b128 v[148:151], v160
	ds_read_b128 v[152:155], v160 offset:1024
	ds_read_b128 v[156:159], v160 offset:2048
	ds_read_b128 v[160:163], v160 offset:3072
	s_add_u32 s24, s66, 0x40000
	s_addc_u32 s25, s67, 0
	s_mov_b32 m0, s56
	v_lshl_add_u64 v[226:227], s[24:25], 0, v[168:169]
	ds_read_b128 v[176:179], v194 offset:32768
	ds_read_b128 v[180:183], v194 offset:33792
	ds_read_b128 v[202:205], v194 offset:34816
	ds_read_b128 v[206:209], v194 offset:35840
	ds_read_b128 v[210:213], v194 offset:36864
	ds_read_b128 v[214:217], v194 offset:37888
	ds_read_b128 v[218:221], v194 offset:38912
	ds_read_b128 v[222:225], v194 offset:39936
	global_load_lds_dwordx4 v[226:227], off
	v_lshl_add_u64 v[226:227], s[24:25], 0, v[166:167]
	s_mov_b32 m0, s70
	s_nop 0
	global_load_lds_dwordx4 v[226:227], off
	s_waitcnt vmcnt(8)
	s_waitcnt lgkmcnt(0)
	s_barrier
	v_mfma_i32_16x16x64_i8 v[128:131], v[132:135], v[176:179], v[128:131]
	v_mfma_i32_16x16x64_i8 v[120:123], v[140:143], v[176:179], v[120:123]
	v_mfma_i32_16x16x64_i8 v[112:115], v[132:135], v[202:205], v[112:115]
	v_mfma_i32_16x16x64_i8 v[104:107], v[140:143], v[202:205], v[104:107]
	v_mfma_i32_16x16x64_i8 v[96:99], v[132:135], v[210:213], v[96:99]
	v_mfma_i32_16x16x64_i8 v[88:91], v[140:143], v[210:213], v[88:91]
	v_mfma_i32_16x16x64_i8 v[80:83], v[132:135], v[218:221], v[80:83]
	v_mfma_i32_16x16x64_i8 v[72:75], v[140:143], v[218:221], v[72:75]
	s_nop 0
	v_mfma_i32_16x16x64_i8 v[128:131], v[136:139], v[180:183], v[128:131]
	v_mfma_i32_16x16x64_i8 v[120:123], v[144:147], v[180:183], v[120:123]
	v_mfma_i32_16x16x64_i8 v[112:115], v[136:139], v[206:209], v[112:115]
	v_mfma_i32_16x16x64_i8 v[104:107], v[144:147], v[206:209], v[104:107]
	v_mfma_i32_16x16x64_i8 v[96:99], v[136:139], v[214:217], v[96:99]
	v_mfma_i32_16x16x64_i8 v[88:91], v[144:147], v[214:217], v[88:91]
	v_mfma_i32_16x16x64_i8 v[80:83], v[136:139], v[222:225], v[80:83]
	v_mfma_i32_16x16x64_i8 v[72:75], v[144:147], v[222:225], v[72:75]
	v_mfma_i32_16x16x64_i8 v[124:127], v[148:151], v[176:179], v[124:127]
	v_mfma_i32_16x16x64_i8 v[116:119], v[156:159], v[176:179], v[116:119]
	v_mfma_i32_16x16x64_i8 v[108:111], v[148:151], v[202:205], v[108:111]
	v_mfma_i32_16x16x64_i8 v[100:103], v[156:159], v[202:205], v[100:103]
	v_mfma_i32_16x16x64_i8 v[92:95], v[148:151], v[210:213], v[92:95]
	v_mfma_i32_16x16x64_i8 v[84:87], v[156:159], v[210:213], v[84:87]
	v_mfma_i32_16x16x64_i8 v[76:79], v[148:151], v[218:221], v[76:79]
	v_mfma_i32_16x16x64_i8 v[68:71], v[156:159], v[218:221], v[68:71]
	s_nop 0
	v_mfma_i32_16x16x64_i8 v[124:127], v[152:155], v[180:183], v[124:127]
	v_mfma_i32_16x16x64_i8 v[116:119], v[160:163], v[180:183], v[116:119]
	v_mfma_i32_16x16x64_i8 v[108:111], v[152:155], v[206:209], v[108:111]
	v_mfma_i32_16x16x64_i8 v[100:103], v[160:163], v[206:209], v[100:103]
	v_mfma_i32_16x16x64_i8 v[92:95], v[152:155], v[214:217], v[92:95]
	v_mfma_i32_16x16x64_i8 v[84:87], v[160:163], v[214:217], v[84:87]
	v_mfma_i32_16x16x64_i8 v[76:79], v[152:155], v[222:225], v[76:79]
	v_mfma_i32_16x16x64_i8 v[68:71], v[160:163], v[222:225], v[68:71]
	s_barrier
	s_add_i32 s21, s21, s18
	v_lshl_add_u64 v[226:227], s[64:65], 0, v[2:3]
	s_mov_b32 m0, s21
	ds_read_b128 v[176:179], v194 offset:49152
	ds_read_b128 v[180:183], v194 offset:50176
	ds_read_b128 v[202:205], v194 offset:51200
	ds_read_b128 v[206:209], v194 offset:52224
	ds_read_b128 v[210:213], v194 offset:53248
	ds_read_b128 v[214:217], v194 offset:54272
	ds_read_b128 v[218:221], v194 offset:55296
	ds_read_b128 v[222:225], v194 offset:56320
	global_load_lds_dwordx4 v[226:227], off
	s_add_i32 m0, s21, 0x2000
	s_add_u32 s24, s64, 0x40000
	v_lshl_add_u64 v[226:227], s[64:65], 0, v[164:165]
	s_addc_u32 s25, s65, 0
	s_add_i32 s21, s30, s18
	global_load_lds_dwordx4 v[226:227], off
	v_lshl_add_u64 v[226:227], s[24:25], 0, v[2:3]
	s_mov_b32 m0, s21
	s_nop 0
	global_load_lds_dwordx4 v[226:227], off
	v_lshl_add_u64 v[226:227], s[24:25], 0, v[164:165]
	s_add_i32 m0, s21, 0x2000
	s_nop 0
	global_load_lds_dwordx4 v[226:227], off
	v_lshl_add_u64 v[226:227], s[62:63], 0, v[168:169]
	s_mov_b32 m0, s71
	s_nop 0
	global_load_lds_dwordx4 v[226:227], off
	v_lshl_add_u64 v[226:227], s[62:63], 0, v[166:167]
	s_mov_b32 m0, s72
	s_nop 0
	global_load_lds_dwordx4 v[226:227], off
	s_waitcnt vmcnt(8)
	s_waitcnt lgkmcnt(0)
	s_barrier
	v_mfma_i32_16x16x64_i8 v[64:67], v[132:135], v[176:179], v[64:67]
	v_mfma_i32_16x16x64_i8 v[56:59], v[140:143], v[176:179], v[56:59]
	v_mfma_i32_16x16x64_i8 v[48:51], v[132:135], v[202:205], v[48:51]
	v_mfma_i32_16x16x64_i8 v[40:43], v[140:143], v[202:205], v[40:43]
	v_mfma_i32_16x16x64_i8 v[32:35], v[132:135], v[210:213], v[32:35]
	v_mfma_i32_16x16x64_i8 v[24:27], v[140:143], v[210:213], v[24:27]
	v_mfma_i32_16x16x64_i8 v[16:19], v[132:135], v[218:221], v[16:19]
	v_mfma_i32_16x16x64_i8 v[8:11], v[140:143], v[218:221], v[8:11]
	s_nop 0
	v_mfma_i32_16x16x64_i8 v[64:67], v[136:139], v[180:183], v[64:67]
	v_mfma_i32_16x16x64_i8 v[56:59], v[144:147], v[180:183], v[56:59]
	v_mfma_i32_16x16x64_i8 v[48:51], v[136:139], v[206:209], v[48:51]
	v_mfma_i32_16x16x64_i8 v[40:43], v[144:147], v[206:209], v[40:43]
	v_mfma_i32_16x16x64_i8 v[32:35], v[136:139], v[214:217], v[32:35]
	v_mfma_i32_16x16x64_i8 v[24:27], v[144:147], v[214:217], v[24:27]
	v_mfma_i32_16x16x64_i8 v[16:19], v[136:139], v[222:225], v[16:19]
	v_mfma_i32_16x16x64_i8 v[8:11], v[144:147], v[222:225], v[8:11]
	v_mfma_i32_16x16x64_i8 v[60:63], v[148:151], v[176:179], v[60:63]
	v_mfma_i32_16x16x64_i8 v[52:55], v[156:159], v[176:179], v[52:55]
	v_mfma_i32_16x16x64_i8 v[44:47], v[148:151], v[202:205], v[44:47]
	v_mfma_i32_16x16x64_i8 v[36:39], v[156:159], v[202:205], v[36:39]
	v_mfma_i32_16x16x64_i8 v[28:31], v[148:151], v[210:213], v[28:31]
	v_mfma_i32_16x16x64_i8 v[20:23], v[156:159], v[210:213], v[20:23]
	v_mfma_i32_16x16x64_i8 v[12:15], v[148:151], v[218:221], v[12:15]
	v_mfma_i32_16x16x64_i8 v[4:7], v[156:159], v[218:221], v[4:7]
	s_nop 0
	v_mfma_i32_16x16x64_i8 v[60:63], v[152:155], v[180:183], v[60:63]
	v_mfma_i32_16x16x64_i8 v[52:55], v[160:163], v[180:183], v[52:55]
	v_mfma_i32_16x16x64_i8 v[44:47], v[152:155], v[206:209], v[44:47]
	v_mfma_i32_16x16x64_i8 v[36:39], v[160:163], v[206:209], v[36:39]
	v_mfma_i32_16x16x64_i8 v[28:31], v[152:155], v[214:217], v[28:31]
	v_mfma_i32_16x16x64_i8 v[20:23], v[160:163], v[214:217], v[20:23]
	v_mfma_i32_16x16x64_i8 v[12:15], v[152:155], v[222:225], v[12:15]
	v_mfma_i32_16x16x64_i8 v[4:7], v[160:163], v[222:225], v[4:7]
	s_barrier
	s_add_i32 s13, s13, 2
	s_add_u32 s60, s60, 0x100
	s_addc_u32 s61, s61, 0
	s_cmp_gt_u32 s13, 13
	s_cbranch_scc1 .LBB0_1279

; #define G_STAGE(bufoff, gbase, voff) do { _Pragma("unroll") for (int _i = 0; _i < 2; ++_i) \
;         __builtin_amdgcn_global_load_lds((const unsigned*)((const char*)(gbase) + (voff)[_i]), (LAS unsigned*)(lds + (bufoff) + ldsw + _i * 8192), 16, 0, 0); } while (0)
; #define G_LDA(dst, b, h) do { _Pragma("unroll") for (int m = 0; m < 4; ++m) { const i32x4 _p0 = *(const LAS i32x4*)(lds + G_SA(b, h) + aoff + m * 2048), _p1 = *(const LAS i32x4*)(lds + G_SA(b, h) + aoff + m * 2048 + 1024); \
;         dst[m] = __builtin_shufflevector(_p0, _p1, 0, 1, 2, 3, 4, 5, 6, 7); } } while (0)
; #define G_LDB(dst, b, h) do { _Pragma("unroll") for (int n = 0; n < 2; ++n) { const i32x4 _p0 = *(const LAS i32x4*)(lds + G_SB(b, h) + boff + n * 2048), _p1 = *(const LAS i32x4*)(lds + G_SB(b, h) + boff + n * 2048 + 1024); \
;         dst[n] = __builtin_shufflevector(_p0, _p1, 0, 1, 2, 3, 4, 5, 6, 7); } } while (0)
; #define G_WAIT_V(n) asm volatile("s_waitcnt vmcnt(" #n ")" ::: "memory")
; #define G_WAIT_L(n) asm volatile("s_waitcnt lgkmcnt(" #n ")" ::: "memory")
; #define G_BAR __builtin_amdgcn_s_barrier()
; #define G_SCHED __builtin_amdgcn_sched_barrier(0)
; template <int NS, int MODE  , class Epi>
; __device__ __forceinline__ void gemm_phase(LAS unsigned char* lds, const Gemm g, const StaticOrder& S, const Epi& E) {
;     ...
;             G_LDB(B0, 0, 0); G_LDB(B1, 0, 1); G_SCHED; G_LDA(At, 0, 0); G_STAGE(G_SA(1, 1), a1 + hstep, voffA);
;             G_WAIT_V(8); G_WAIT_L(0); G_BAR; G_MMA(0, 0, At, B0); G_MMA(0, 1, At, B1); G_BAR; G_SCHED;
;             G_LDA(At, 0, 1); G_STAGE(G_SB(0, 0), b2, voffB); G_STAGE(G_SB(0, 1), b2 + hstep, voffB); G_STAGE(G_SA(0, 0), a2, voffA);
;             G_WAIT_V(8); G_WAIT_L(0); G_BAR; G_MMA(1, 0, At, B0); G_MMA(1, 1, At, B1); G_BAR; G_SCHED;
.LBB0_1357:
	s_add_i32 s25, 0, 0x10000
	s_add_i32 s30, 0, 0x14000
	v_add_u32_e32 v4, s25, v214
	v_add_u32_e32 v16, s30, v214
	ds_read_b128 v[20:23], v4
	ds_read_b128 v[24:27], v4 offset:1024
	ds_read_b128 v[28:31], v4 offset:2048
	ds_read_b128 v[32:35], v4 offset:3072
	ds_read_b128 v[4:7], v16
	ds_read_b128 v[8:11], v16 offset:1024
	ds_read_b128 v[12:15], v16 offset:2048
	ds_read_b128 v[16:19], v16 offset:3072
	v_lshl_add_u64 v[176:177], v[164:165], 0, s[48:49]
	s_add_i32 m0, s19, 0xc000
	ds_read_b128 v[188:191], v216
	ds_read_b128 v[192:195], v216 offset:1024
	ds_read_b128 v[196:199], v216 offset:2048
	ds_read_b128 v[200:203], v216 offset:3072
	ds_read_b128 v[204:207], v216 offset:4096
	ds_read_b128 v[208:211], v216 offset:5120
	ds_read_b128 v[218:221], v216 offset:6144
	ds_read_b128 v[222:225], v216 offset:7168
	global_load_lds_dwordx4 v[176:177], off
	v_lshl_add_u64 v[176:177], v[166:167], 0, s[48:49]
	s_add_i32 m0, s19, 0xe000
	s_nop 0
	global_load_lds_dwordx4 v[176:177], off
	s_waitcnt vmcnt(8)
	s_waitcnt lgkmcnt(0)
	s_barrier
	v_mfma_scale_f32_16x16x128_f8f6f4 v[160:163], v[20:27], v[188:195], v[160:163], v212, v212 op_sel_hi:[0,0,0]
	v_mfma_scale_f32_16x16x128_f8f6f4 v[156:159], v[28:35], v[188:195], v[156:159], v212, v212 op_sel_hi:[0,0,0]
	v_mfma_scale_f32_16x16x128_f8f6f4 v[144:147], v[20:27], v[196:203], v[144:147], v212, v212 op_sel_hi:[0,0,0]
	v_mfma_scale_f32_16x16x128_f8f6f4 v[140:143], v[28:35], v[196:203], v[140:143], v212, v212 op_sel_hi:[0,0,0]
	v_mfma_scale_f32_16x16x128_f8f6f4 v[128:131], v[20:27], v[204:211], v[128:131], v212, v212 op_sel_hi:[0,0,0]
	v_mfma_scale_f32_16x16x128_f8f6f4 v[124:127], v[28:35], v[204:211], v[124:127], v212, v212 op_sel_hi:[0,0,0]
	v_mfma_scale_f32_16x16x128_f8f6f4 v[112:115], v[20:27], v[218:225], v[112:115], v212, v212 op_sel_hi:[0,0,0]
	v_mfma_scale_f32_16x16x128_f8f6f4 v[108:111], v[28:35], v[218:225], v[108:111], v212, v212 op_sel_hi:[0,0,0]
	v_mfma_scale_f32_16x16x128_f8f6f4 v[152:155], v[4:11], v[188:195], v[152:155], v212, v212 op_sel_hi:[0,0,0]
	v_mfma_scale_f32_16x16x128_f8f6f4 v[148:151], v[12:19], v[188:195], v[148:151], v212, v212 op_sel_hi:[0,0,0]
	v_mfma_scale_f32_16x16x128_f8f6f4 v[136:139], v[4:11], v[196:203], v[136:139], v212, v212 op_sel_hi:[0,0,0]
	v_mfma_scale_f32_16x16x128_f8f6f4 v[132:135], v[12:19], v[196:203], v[132:135], v212, v212 op_sel_hi:[0,0,0]
	v_mfma_scale_f32_16x16x128_f8f6f4 v[120:123], v[4:11], v[204:211], v[120:123], v212, v212 op_sel_hi:[0,0,0]
	v_mfma_scale_f32_16x16x128_f8f6f4 v[116:119], v[12:19], v[204:211], v[116:119], v212, v212 op_sel_hi:[0,0,0]
	v_mfma_scale_f32_16x16x128_f8f6f4 v[104:107], v[4:11], v[218:225], v[104:107], v212, v212 op_sel_hi:[0,0,0]
	v_mfma_scale_f32_16x16x128_f8f6f4 v[100:103], v[12:19], v[218:225], v[100:103], v212, v212 op_sel_hi:[0,0,0]
	s_barrier
	s_add_i32 s25, s25, s18
	v_lshl_add_u64 v[176:177], s[60:61], 0, v[2:3]
	s_mov_b32 m0, s25
	ds_read_b128 v[188:191], v216 offset:16384
	ds_read_b128 v[192:195], v216 offset:17408
	ds_read_b128 v[196:199], v216 offset:18432
	ds_read_b128 v[200:203], v216 offset:19456
	ds_read_b128 v[204:207], v216 offset:20480
	ds_read_b128 v[208:211], v216 offset:21504
	ds_read_b128 v[218:221], v216 offset:22528
	ds_read_b128 v[222:225], v216 offset:23552
	global_load_lds_dwordx4 v[176:177], off
	s_add_i32 m0, s25, 0x2000
	v_lshl_add_u64 v[176:177], s[60:61], 0, v[172:173]
	s_add_u32 s60, s60, 0xb0000
	s_addc_u32 s61, s61, 0
	s_add_i32 s25, s30, s18
	global_load_lds_dwordx4 v[176:177], off
	v_lshl_add_u64 v[176:177], s[60:61], 0, v[2:3]
	s_mov_b32 m0, s25
	s_nop 0
	global_load_lds_dwordx4 v[176:177], off
	v_lshl_add_u64 v[176:177], s[60:61], 0, v[172:173]
	s_add_i32 m0, s25, 0x2000
	s_nop 0
	global_load_lds_dwordx4 v[176:177], off
	v_lshl_add_u64 v[176:177], s[58:59], 0, v[168:169]
	s_mov_b32 m0, s19
	s_nop 0
	global_load_lds_dwordx4 v[176:177], off
	v_lshl_add_u64 v[176:177], s[58:59], 0, v[170:171]
	s_mov_b32 m0, s29
	s_nop 0
	global_load_lds_dwordx4 v[176:177], off
	s_waitcnt vmcnt(8)
	s_waitcnt lgkmcnt(0)
	s_barrier
	v_mfma_scale_f32_16x16x128_f8f6f4 v[96:99], v[20:27], v[188:195], v[96:99], v212, v212 op_sel_hi:[0,0,0]
	v_mfma_scale_f32_16x16x128_f8f6f4 v[92:95], v[28:35], v[188:195], v[92:95], v212, v212 op_sel_hi:[0,0,0]
	v_mfma_scale_f32_16x16x128_f8f6f4 v[80:83], v[20:27], v[196:203], v[80:83], v212, v212 op_sel_hi:[0,0,0]
	v_mfma_scale_f32_16x16x128_f8f6f4 v[76:79], v[28:35], v[196:203], v[76:79], v212, v212 op_sel_hi:[0,0,0]
	v_mfma_scale_f32_16x16x128_f8f6f4 v[64:67], v[20:27], v[204:211], v[64:67], v212, v212 op_sel_hi:[0,0,0]
	v_mfma_scale_f32_16x16x128_f8f6f4 v[60:63], v[28:35], v[204:211], v[60:63], v212, v212 op_sel_hi:[0,0,0]
	v_mfma_scale_f32_16x16x128_f8f6f4 v[48:51], v[20:27], v[218:225], v[48:51], v212, v212 op_sel_hi:[0,0,0]
	v_mfma_scale_f32_16x16x128_f8f6f4 v[44:47], v[28:35], v[218:225], v[44:47], v212, v212 op_sel_hi:[0,0,0]
	v_mfma_scale_f32_16x16x128_f8f6f4 v[88:91], v[4:11], v[188:195], v[88:91], v212, v212 op_sel_hi:[0,0,0]
	v_mfma_scale_f32_16x16x128_f8f6f4 v[84:87], v[12:19], v[188:195], v[84:87], v212, v212 op_sel_hi:[0,0,0]
	v_mfma_scale_f32_16x16x128_f8f6f4 v[72:75], v[4:11], v[196:203], v[72:75], v212, v212 op_sel_hi:[0,0,0]
	v_mfma_scale_f32_16x16x128_f8f6f4 v[68:71], v[12:19], v[196:203], v[68:71], v212, v212 op_sel_hi:[0,0,0]
	v_mfma_scale_f32_16x16x128_f8f6f4 v[56:59], v[4:11], v[204:211], v[56:59], v212, v212 op_sel_hi:[0,0,0]
	v_mfma_scale_f32_16x16x128_f8f6f4 v[52:55], v[12:19], v[204:211], v[52:55], v212, v212 op_sel_hi:[0,0,0]
	v_mfma_scale_f32_16x16x128_f8f6f4 v[40:43], v[4:11], v[218:225], v[40:43], v212, v212 op_sel_hi:[0,0,0]
	v_mfma_scale_f32_16x16x128_f8f6f4 v[36:39], v[12:19], v[218:225], v[36:39], v212, v212 op_sel_hi:[0,0,0]
	s_barrier
; #define G_STAGE(bufoff, gbase, voff) do { _Pragma("unroll") for (int _i = 0; _i < 2; ++_i) \
;         __builtin_amdgcn_global_load_lds((const unsigned*)((const char*)(gbase) + (voff)[_i]), (LAS unsigned*)(lds + (bufoff) + ldsw + _i * 8192), 16, 0, 0); } while (0)
; #define G_LDA(dst, b, h) do { _Pragma("unroll") for (int m = 0; m < 4; ++m) { const i32x4 _p0 = *(const LAS i32x4*)(lds + G_SA(b, h) + aoff + m * 2048), _p1 = *(const LAS i32x4*)(lds + G_SA(b, h) + aoff + m * 2048 + 1024); \
;         dst[m] = __builtin_shufflevector(_p0, _p1, 0, 1, 2, 3, 4, 5, 6, 7); } } while (0)
; #define G_LDB(dst, b, h) do { _Pragma("unroll") for (int n = 0; n < 2; ++n) { const i32x4 _p0 = *(const LAS i32x4*)(lds + G_SB(b, h) + boff + n * 2048), _p1 = *(const LAS i32x4*)(lds + G_SB(b, h) + boff + n * 2048 + 1024); \
;         dst[n] = __builtin_shufflevector(_p0, _p1, 0, 1, 2, 3, 4, 5, 6, 7); } } while (0)
; #define G_WAIT_V(n) asm volatile("s_waitcnt vmcnt(" #n ")" ::: "memory")
; #define G_WAIT_L(n) asm volatile("s_waitcnt lgkmcnt(" #n ")" ::: "memory")
; #define G_BAR __builtin_amdgcn_s_barrier()
; #define G_SCHED __builtin_amdgcn_sched_barrier(0)
; template <int NS, int MODE  , class Epi>
; __device__ __forceinline__ void gemm_phase(LAS unsigned char* lds, const Gemm g, const StaticOrder& S, const Epi& E) {
;     ...
;             G_LDB(B0, 1, 0); G_LDB(B1, 1, 1); G_SCHED; G_LDA(At, 1, 0); G_STAGE(G_SA(0, 1), a2 + hstep, voffA);
;             G_WAIT_V(8); G_WAIT_L(0); G_BAR; G_MMA(0, 0, At, B0); G_MMA(0, 1, At, B1); G_BAR; G_SCHED;
;             G_LDA(At, 1, 1); G_STAGE(G_SB(1, 0), b3, voffB); G_STAGE(G_SB(1, 1), b3 + hstep, voffB); G_STAGE(G_SA(1, 0), a3, voffA);
;             G_WAIT_V(8); G_WAIT_L(0); G_BAR; G_MMA(1, 0, At, B0); G_MMA(1, 1, At, B1); G_BAR; G_SCHED;
	s_add_i32 s25, 0, 0x18000
	s_add_i32 s35, 0, 0x1c000
	v_add_u32_e32 v16, s25, v214
	v_add_u32_e32 v32, s35, v214
	ds_read_b128 v[4:7], v16
	ds_read_b128 v[8:11], v16 offset:1024
	ds_read_b128 v[12:15], v16 offset:2048
	ds_read_b128 v[16:19], v16 offset:3072
	ds_read_b128 v[20:23], v32
	ds_read_b128 v[24:27], v32 offset:1024
	ds_read_b128 v[28:31], v32 offset:2048
	ds_read_b128 v[32:35], v32 offset:3072
	s_add_u32 s30, s58, 0xb0000
	s_addc_u32 s31, s59, 0
	s_mov_b32 m0, s56
	v_lshl_add_u64 v[176:177], s[30:31], 0, v[168:169]
	ds_read_b128 v[188:191], v216 offset:32768
	ds_read_b128 v[192:195], v216 offset:33792
	ds_read_b128 v[196:199], v216 offset:34816
	ds_read_b128 v[200:203], v216 offset:35840
	ds_read_b128 v[204:207], v216 offset:36864
	ds_read_b128 v[208:211], v216 offset:37888
	ds_read_b128 v[218:221], v216 offset:38912
	ds_read_b128 v[222:225], v216 offset:39936
	global_load_lds_dwordx4 v[176:177], off
	v_lshl_add_u64 v[176:177], s[30:31], 0, v[170:171]
	s_mov_b32 m0, s62
	s_nop 0
	global_load_lds_dwordx4 v[176:177], off
	s_waitcnt vmcnt(8)
	s_waitcnt lgkmcnt(0)
	s_barrier
	v_mfma_scale_f32_16x16x128_f8f6f4 v[160:163], v[4:11], v[188:195], v[160:163], v212, v212 op_sel_hi:[0,0,0]
	v_mfma_scale_f32_16x16x128_f8f6f4 v[156:159], v[12:19], v[188:195], v[156:159], v212, v212 op_sel_hi:[0,0,0]
	v_mfma_scale_f32_16x16x128_f8f6f4 v[144:147], v[4:11], v[196:203], v[144:147], v212, v212 op_sel_hi:[0,0,0]
	v_mfma_scale_f32_16x16x128_f8f6f4 v[140:143], v[12:19], v[196:203], v[140:143], v212, v212 op_sel_hi:[0,0,0]
	v_mfma_scale_f32_16x16x128_f8f6f4 v[128:131], v[4:11], v[204:211], v[128:131], v212, v212 op_sel_hi:[0,0,0]
	v_mfma_scale_f32_16x16x128_f8f6f4 v[124:127], v[12:19], v[204:211], v[124:127], v212, v212 op_sel_hi:[0,0,0]
	v_mfma_scale_f32_16x16x128_f8f6f4 v[112:115], v[4:11], v[218:225], v[112:115], v212, v212 op_sel_hi:[0,0,0]
	v_mfma_scale_f32_16x16x128_f8f6f4 v[108:111], v[12:19], v[218:225], v[108:111], v212, v212 op_sel_hi:[0,0,0]
	v_mfma_scale_f32_16x16x128_f8f6f4 v[152:155], v[20:27], v[188:195], v[152:155], v212, v212 op_sel_hi:[0,0,0]
	v_mfma_scale_f32_16x16x128_f8f6f4 v[148:151], v[28:35], v[188:195], v[148:151], v212, v212 op_sel_hi:[0,0,0]
	v_mfma_scale_f32_16x16x128_f8f6f4 v[136:139], v[20:27], v[196:203], v[136:139], v212, v212 op_sel_hi:[0,0,0]
	v_mfma_scale_f32_16x16x128_f8f6f4 v[132:135], v[28:35], v[196:203], v[132:135], v212, v212 op_sel_hi:[0,0,0]
	v_mfma_scale_f32_16x16x128_f8f6f4 v[120:123], v[20:27], v[204:211], v[120:123], v212, v212 op_sel_hi:[0,0,0]
	v_mfma_scale_f32_16x16x128_f8f6f4 v[116:119], v[28:35], v[204:211], v[116:119], v212, v212 op_sel_hi:[0,0,0]
	v_mfma_scale_f32_16x16x128_f8f6f4 v[104:107], v[20:27], v[218:225], v[104:107], v212, v212 op_sel_hi:[0,0,0]
	v_mfma_scale_f32_16x16x128_f8f6f4 v[100:103], v[28:35], v[218:225], v[100:103], v212, v212 op_sel_hi:[0,0,0]
	s_barrier
	s_add_i32 s25, s25, s18
	v_lshl_add_u64 v[176:177], s[54:55], 0, v[2:3]
	s_mov_b32 m0, s25
	ds_read_b128 v[188:191], v216 offset:49152
	ds_read_b128 v[192:195], v216 offset:50176
	ds_read_b128 v[196:199], v216 offset:51200
	ds_read_b128 v[200:203], v216 offset:52224
	ds_read_b128 v[204:207], v216 offset:53248
	ds_read_b128 v[208:211], v216 offset:54272
	ds_read_b128 v[218:221], v216 offset:55296
	ds_read_b128 v[222:225], v216 offset:56320
	global_load_lds_dwordx4 v[176:177], off
	s_add_i32 m0, s25, 0x2000
	s_add_u32 s30, s54, 0xb0000
	v_lshl_add_u64 v[176:177], s[54:55], 0, v[172:173]
	s_addc_u32 s31, s55, 0
	s_add_i32 s25, s35, s18
	global_load_lds_dwordx4 v[176:177], off
	v_lshl_add_u64 v[176:177], s[30:31], 0, v[2:3]
	s_mov_b32 m0, s25
	s_nop 0
	global_load_lds_dwordx4 v[176:177], off
	v_lshl_add_u64 v[176:177], s[30:31], 0, v[172:173]
	s_add_i32 m0, s25, 0x2000
	s_nop 0
	global_load_lds_dwordx4 v[176:177], off
	v_lshl_add_u64 v[176:177], s[52:53], 0, v[168:169]
	s_mov_b32 m0, s65
	s_nop 0
	global_load_lds_dwordx4 v[176:177], off
	v_lshl_add_u64 v[176:177], s[52:53], 0, v[170:171]
	s_mov_b32 m0, s66
	s_nop 0
	global_load_lds_dwordx4 v[176:177], off
	s_waitcnt vmcnt(8)
	s_waitcnt lgkmcnt(0)
	s_barrier
	v_mfma_scale_f32_16x16x128_f8f6f4 v[96:99], v[4:11], v[188:195], v[96:99], v212, v212 op_sel_hi:[0,0,0]
	v_mfma_scale_f32_16x16x128_f8f6f4 v[92:95], v[12:19], v[188:195], v[92:95], v212, v212 op_sel_hi:[0,0,0]
	v_mfma_scale_f32_16x16x128_f8f6f4 v[80:83], v[4:11], v[196:203], v[80:83], v212, v212 op_sel_hi:[0,0,0]
	v_mfma_scale_f32_16x16x128_f8f6f4 v[76:79], v[12:19], v[196:203], v[76:79], v212, v212 op_sel_hi:[0,0,0]
	v_mfma_scale_f32_16x16x128_f8f6f4 v[64:67], v[4:11], v[204:211], v[64:67], v212, v212 op_sel_hi:[0,0,0]
	v_mfma_scale_f32_16x16x128_f8f6f4 v[60:63], v[12:19], v[204:211], v[60:63], v212, v212 op_sel_hi:[0,0,0]
	v_mfma_scale_f32_16x16x128_f8f6f4 v[48:51], v[4:11], v[218:225], v[48:51], v212, v212 op_sel_hi:[0,0,0]
	v_mfma_scale_f32_16x16x128_f8f6f4 v[44:47], v[12:19], v[218:225], v[44:47], v212, v212 op_sel_hi:[0,0,0]
	v_mfma_scale_f32_16x16x128_f8f6f4 v[88:91], v[20:27], v[188:195], v[88:91], v212, v212 op_sel_hi:[0,0,0]
	v_mfma_scale_f32_16x16x128_f8f6f4 v[84:87], v[28:35], v[188:195], v[84:87], v212, v212 op_sel_hi:[0,0,0]
	v_mfma_scale_f32_16x16x128_f8f6f4 v[72:75], v[20:27], v[196:203], v[72:75], v212, v212 op_sel_hi:[0,0,0]
	v_mfma_scale_f32_16x16x128_f8f6f4 v[68:71], v[28:35], v[196:203], v[68:71], v212, v212 op_sel_hi:[0,0,0]
	v_mfma_scale_f32_16x16x128_f8f6f4 v[56:59], v[20:27], v[204:211], v[56:59], v212, v212 op_sel_hi:[0,0,0]
	v_mfma_scale_f32_16x16x128_f8f6f4 v[52:55], v[28:35], v[204:211], v[52:55], v212, v212 op_sel_hi:[0,0,0]
	v_mfma_scale_f32_16x16x128_f8f6f4 v[40:43], v[20:27], v[218:225], v[40:43], v212, v212 op_sel_hi:[0,0,0]
	v_mfma_scale_f32_16x16x128_f8f6f4 v[36:39], v[28:35], v[218:225], v[36:39], v212, v212 op_sel_hi:[0,0,0]
	s_barrier
	s_add_i32 s24, s24, 2
	s_add_u32 s48, s48, 0x100
	s_addc_u32 s49, s49, 0
	s_cmp_gt_u32 s24, 41
	s_cbranch_scc1 .LBB0_1360
